# back-edge rotation (7.11) on 7 K-loops: loop-back barrier moved to loop head, counter/exit test/header SALU before it, exit-path barrier copy
# baseline (speedup 1.0000x reference)
; #define G8_STA(bufoff, ptr, sg, h) G8_STAGE1(bufoff, (ptr) + (h) * ((sg) ? hA1 : hA0), ((sg) ? voffA1 : voffA0), ((sg) ? r64A1 : r64A0))
; #define G8_STB(bufoff, ptr, sg, h) G8_STAGE1(bufoff, (ptr) + (h) * ((sg) ? hB1 : hB0), ((sg) ? voffB1 : voffB0), ((sg) ? r64B1 : r64B0))
; #define G8_LDA(dst, b, h) do { _Pragma("unroll") for (int m = 0; m < 4; ++m) _Pragma("unroll") for (int k = 0; k < 2; ++k) dst[m][k] = *(const LAS bf16x8*)(lds + G8_SA(b, h) + aoff + m * 2048 + k * 1024); } while (0)
; #define G8_LDB(dst, b, h) do { _Pragma("unroll") for (int n = 0; n < 2; ++n) _Pragma("unroll") for (int k = 0; k < 2; ++k) dst[n][k] = *(const LAS bf16x8*)(lds + G8_SB(b, h) + boff + n * 2048 + k * 1024); } while (0)
; #define G8_MMA(ai, bj, At, Bt) do { __builtin_amdgcn_s_setprio(1); _Pragma("unroll") for (int m = 0; m < 4; ++m) _Pragma("unroll") for (int n = 0; n < 2; ++n) _Pragma("unroll") for (int k = 0; k < 2; ++k) \
;         acc[ai][bj][m][n] = __builtin_amdgcn_mfma_f32_16x16x32_bf16(Bt[n][k], At[m][k], acc[ai][bj][m][n], 0, 0, 0); __builtin_amdgcn_s_setprio(0); } while (0)
; #define G8_BAR __builtin_amdgcn_s_barrier()
; template <class P>
; __device__ __forceinline__ void gemm_phase(LAS unsigned char* lds, const P& p, const int G, const int c) {
;     ...
;         for (int t = 0; t < nt; t += 2) {
;             const bool last = (t == nt - 2);
;             const bool sg1 = (NS > 1) && (t + 1 >= nt0);
;             const bool sg2 = (NS > 1) && !last && (t + 2 >= nt0);
;             const char* a1 = sg1 ? cA1 + (long)(t + 1 - nt0) * ksA1 : cA0 + (long)(t + 1) * ksA0;
;             const char* a2 = last ? nA0 : (sg2 ? cA1 + (long)(t + 2 - nt0) * ksA1 : cA0 + (long)(t + 2) * ksA0);
;             const char* b2 = last ? nB0 : (sg2 ? cB1 + (long)(t + 2 - nt0) * ksB1 : cB0 + (long)(t + 2) * ksB0);
;             const char* a3 = a2 + (sg2 ? ksA1 : ksA0); const char* b3 = b2 + (sg2 ? ksB1 : ksB0);
;             G8_LDB(B0, 0, 0); G8_LDB(B1, 0, 1); G8_SCHED; G8_LDA(At, 0, 0); G8_STA(G8_SA(1, 1), a1, sg1, 1);
;             G8_WAIT_V(8); G8_WAIT_L(0); G8_BAR; G8_MMA(0, 0, At, B0); G8_MMA(0, 1, At, B1); G8_BAR; G8_SCHED;
;             G8_LDA(At, 0, 1); G8_STB(G8_SB(0, 0), b2, sg2, 0); G8_STB(G8_SB(0, 1), b2, sg2, 1); G8_STA(G8_SA(0, 0), a2, sg2, 0);
;             G8_WAIT_V(8); G8_WAIT_L(0); G8_BAR; G8_MMA(1, 0, At, B0); G8_MMA(1, 1, At, B1); G8_BAR; G8_SCHED;
.LBB0_155:
	s_barrier
	ds_read_b128 v[56:59], v173
	ds_read_b128 v[60:63], v173 offset:1024
	ds_read_b128 v[176:179], v173 offset:2048
	ds_read_b128 v[180:183], v173 offset:3072
	ds_read_b128 v[184:187], v174
	ds_read_b128 v[188:191], v174 offset:1024
	ds_read_b128 v[192:195], v174 offset:2048
	ds_read_b128 v[196:199], v174 offset:3072
	s_add_u32 s53, s82, s84
	s_addc_u32 s56, s83, s85
	s_add_u32 s53, s53, 0x820000
	s_addc_u32 s56, s56, 0
	s_cmp_eq_u32 s84, 0x38e0000
	s_cselect_b32 s57, s18, s56
	s_cselect_b32 s56, s19, s53
	s_cselect_b32 s65, s30, s29
	s_cselect_b32 s64, s31, s28
	v_lshl_add_u64 v[64:65], v[54:55], 0, s[84:85]
	s_mov_b64 s[66:67], 0x414000
	v_lshl_add_u64 v[234:235], v[64:65], 0, s[66:67]
	s_add_i32 m0, s27, 0xc000
	s_mov_b64 s[66:67], 0x416000
	ds_read_b128 v[200:203], v175
	ds_read_b128 v[204:207], v175 offset:1024
	ds_read_b128 v[210:213], v175 offset:2048
	ds_read_b128 v[214:217], v175 offset:3072
	ds_read_b128 v[218:221], v175 offset:4096
	ds_read_b128 v[222:225], v175 offset:5120
	ds_read_b128 v[226:229], v175 offset:6144
	ds_read_b128 v[230:233], v175 offset:7168
	global_load_lds_dwordx4 v[234:235], off
	v_lshl_add_u64 v[64:65], v[64:65], 0, s[66:67]
	s_add_i32 m0, s27, 0xe000
	s_nop 0
	global_load_lds_dwordx4 v[64:65], off
	s_waitcnt vmcnt(8)
	s_waitcnt lgkmcnt(0)
	s_barrier
	s_waitcnt lgkmcnt(0)
	v_mfma_f32_16x16x32_bf16 v[98:101], v[56:59], v[200:203], v[98:101]
	v_mfma_f32_16x16x32_bf16 v[138:141], v[176:179], v[200:203], v[138:141]
	v_mfma_f32_16x16x32_bf16 v[70:73], v[56:59], v[210:213], v[70:73]
	v_mfma_f32_16x16x32_bf16 v[114:117], v[176:179], v[210:213], v[114:117]
	v_mfma_f32_16x16x32_bf16 v[46:49], v[56:59], v[218:221], v[46:49]
	v_mfma_f32_16x16x32_bf16 v[110:113], v[176:179], v[218:221], v[110:113]
	v_mfma_f32_16x16x32_bf16 v[38:41], v[56:59], v[226:229], v[38:41]
	v_mfma_f32_16x16x32_bf16 v[130:133], v[176:179], v[226:229], v[130:133]
	v_mfma_f32_16x16x32_bf16 v[98:101], v[60:63], v[204:207], v[98:101]
	v_mfma_f32_16x16x32_bf16 v[138:141], v[180:183], v[204:207], v[138:141]
	v_mfma_f32_16x16x32_bf16 v[70:73], v[60:63], v[214:217], v[70:73]
	v_mfma_f32_16x16x32_bf16 v[114:117], v[180:183], v[214:217], v[114:117]
	v_mfma_f32_16x16x32_bf16 v[46:49], v[60:63], v[222:225], v[46:49]
	v_mfma_f32_16x16x32_bf16 v[110:113], v[180:183], v[222:225], v[110:113]
	v_mfma_f32_16x16x32_bf16 v[38:41], v[60:63], v[230:233], v[38:41]
	v_mfma_f32_16x16x32_bf16 v[130:133], v[180:183], v[230:233], v[130:133]
	v_mfma_f32_16x16x32_bf16 v[134:137], v[184:187], v[200:203], v[134:137]
	v_mfma_f32_16x16x32_bf16 v[74:77], v[192:195], v[200:203], v[74:77]
	v_mfma_f32_16x16x32_bf16 v[106:109], v[184:187], v[210:213], v[106:109]
	v_mfma_f32_16x16x32_bf16 v[50:53], v[192:195], v[210:213], v[50:53]
	v_mfma_f32_16x16x32_bf16 v[102:105], v[184:187], v[218:221], v[102:105]
	v_mfma_f32_16x16x32_bf16 v[42:45], v[192:195], v[218:221], v[42:45]
	v_mfma_f32_16x16x32_bf16 v[126:129], v[184:187], v[226:229], v[126:129]
	v_mfma_f32_16x16x32_bf16 v[34:37], v[192:195], v[226:229], v[34:37]
	v_mfma_f32_16x16x32_bf16 v[134:137], v[188:191], v[204:207], v[134:137]
	v_mfma_f32_16x16x32_bf16 v[74:77], v[196:199], v[204:207], v[74:77]
	v_mfma_f32_16x16x32_bf16 v[106:109], v[188:191], v[214:217], v[106:109]
	v_mfma_f32_16x16x32_bf16 v[50:53], v[196:199], v[214:217], v[50:53]
	v_mfma_f32_16x16x32_bf16 v[102:105], v[188:191], v[222:225], v[102:105]
	v_mfma_f32_16x16x32_bf16 v[42:45], v[196:199], v[222:225], v[42:45]
	v_mfma_f32_16x16x32_bf16 v[126:129], v[188:191], v[230:233], v[126:129]
	v_mfma_f32_16x16x32_bf16 v[34:37], v[196:199], v[230:233], v[34:37]
	s_barrier
	s_add_i32 s53, s50, s2
	v_lshl_add_u64 v[234:235], s[64:65], 0, v[142:143]
	s_mov_b32 m0, s53
	ds_read_b128 v[200:203], v175 offset:16384
	ds_read_b128 v[204:207], v175 offset:17408
	ds_read_b128 v[210:213], v175 offset:18432
	ds_read_b128 v[214:217], v175 offset:19456
	ds_read_b128 v[218:221], v175 offset:20480
	ds_read_b128 v[222:225], v175 offset:21504
	ds_read_b128 v[226:229], v175 offset:22528
	ds_read_b128 v[230:233], v175 offset:23552
	global_load_lds_dwordx4 v[234:235], off
	v_lshl_add_u64 v[64:65], v[234:235], 0, s[4:5]
	s_add_i32 m0, s53, 0x2000
	s_add_i32 s53, s51, s2
	global_load_lds_dwordx4 v[64:65], off
	v_lshl_add_u64 v[64:65], v[234:235], 0, s[6:7]
	s_mov_b32 m0, s53
	v_lshl_add_u64 v[236:237], s[56:57], 0, v[144:145]
	global_load_lds_dwordx4 v[64:65], off
	v_lshl_add_u64 v[64:65], v[234:235], 0, s[8:9]
	s_add_i32 m0, s53, 0x2000
	s_nop 0
	global_load_lds_dwordx4 v[64:65], off
	s_mov_b32 m0, s27
	v_lshl_add_u64 v[64:65], v[236:237], 0, s[4:5]
	global_load_lds_dwordx4 v[236:237], off
	s_mov_b32 m0, s33
	s_nop 0
	global_load_lds_dwordx4 v[64:65], off
	s_waitcnt vmcnt(8)
	s_waitcnt lgkmcnt(0)
	s_barrier
	s_waitcnt lgkmcnt(0)
	v_mfma_f32_16x16x32_bf16 v[30:33], v[56:59], v[200:203], v[30:33]
	v_mfma_f32_16x16x32_bf16 v[122:125], v[176:179], v[200:203], v[122:125]
	v_mfma_f32_16x16x32_bf16 v[22:25], v[56:59], v[210:213], v[22:25]
	v_mfma_f32_16x16x32_bf16 v[94:97], v[176:179], v[210:213], v[94:97]
	v_mfma_f32_16x16x32_bf16 v[14:17], v[56:59], v[218:221], v[14:17]
	v_mfma_f32_16x16x32_bf16 v[90:93], v[176:179], v[218:221], v[90:93]
	v_mfma_f32_16x16x32_bf16 v[6:9], v[56:59], v[226:229], v[6:9]
	v_mfma_f32_16x16x32_bf16 v[30:33], v[60:63], v[204:207], v[30:33]
	v_mfma_f32_16x16x32_bf16 v[122:125], v[180:183], v[204:207], v[122:125]
	v_mfma_f32_16x16x32_bf16 v[22:25], v[60:63], v[214:217], v[22:25]
	v_mfma_f32_16x16x32_bf16 v[94:97], v[180:183], v[214:217], v[94:97]
	v_mfma_f32_16x16x32_bf16 v[14:17], v[60:63], v[222:225], v[14:17]
	v_mfma_f32_16x16x32_bf16 v[90:93], v[180:183], v[222:225], v[90:93]
	v_mfma_f32_16x16x32_bf16 v[6:9], v[60:63], v[230:233], v[6:9]
	v_mfma_f32_16x16x32_bf16 v[56:59], v[176:179], v[226:229], v[78:81]
	v_mfma_f32_16x16x32_bf16 v[56:59], v[180:183], v[230:233], v[56:59]
	v_mfma_f32_16x16x32_bf16 v[78:81], v[184:187], v[210:213], v[86:89]
	v_mfma_f32_16x16x32_bf16 v[26:29], v[192:195], v[200:203], v[26:29]
	v_mfma_f32_16x16x32_bf16 v[86:89], v[188:191], v[214:217], v[78:81]
	v_mfma_f32_16x16x32_bf16 v[18:21], v[192:195], v[210:213], v[18:21]
	v_mfma_f32_16x16x32_bf16 v[78:81], v[184:187], v[218:221], v[82:85]
	v_mfma_f32_16x16x32_bf16 v[10:13], v[192:195], v[218:221], v[10:13]
	v_mfma_f32_16x16x32_bf16 v[64:67], v[184:187], v[226:229], v[66:69]
	v_mfma_f32_16x16x32_bf16 v[2:5], v[192:195], v[226:229], v[2:5]
	v_mfma_f32_16x16x32_bf16 v[60:63], v[184:187], v[200:203], v[118:121]
	v_mfma_f32_16x16x32_bf16 v[26:29], v[196:199], v[204:207], v[26:29]
	v_mfma_f32_16x16x32_bf16 v[18:21], v[196:199], v[214:217], v[18:21]
	v_mfma_f32_16x16x32_bf16 v[82:85], v[188:191], v[222:225], v[78:81]
	v_mfma_f32_16x16x32_bf16 v[10:13], v[196:199], v[222:225], v[10:13]
	v_mfma_f32_16x16x32_bf16 v[64:67], v[188:191], v[230:233], v[64:67]
	v_mfma_f32_16x16x32_bf16 v[2:5], v[196:199], v[230:233], v[2:5]
	v_mfma_f32_16x16x32_bf16 v[60:63], v[188:191], v[204:207], v[60:63]
; #define G8_STA(bufoff, ptr, sg, h) G8_STAGE1(bufoff, (ptr) + (h) * ((sg) ? hA1 : hA0), ((sg) ? voffA1 : voffA0), ((sg) ? r64A1 : r64A0))
; #define G8_STB(bufoff, ptr, sg, h) G8_STAGE1(bufoff, (ptr) + (h) * ((sg) ? hB1 : hB0), ((sg) ? voffB1 : voffB0), ((sg) ? r64B1 : r64B0))
; #define G8_LDA(dst, b, h) do { _Pragma("unroll") for (int m = 0; m < 4; ++m) _Pragma("unroll") for (int k = 0; k < 2; ++k) dst[m][k] = *(const LAS bf16x8*)(lds + G8_SA(b, h) + aoff + m * 2048 + k * 1024); } while (0)
; #define G8_LDB(dst, b, h) do { _Pragma("unroll") for (int n = 0; n < 2; ++n) _Pragma("unroll") for (int k = 0; k < 2; ++k) dst[n][k] = *(const LAS bf16x8*)(lds + G8_SB(b, h) + boff + n * 2048 + k * 1024); } while (0)
; #define G8_MMA(ai, bj, At, Bt) do { __builtin_amdgcn_s_setprio(1); _Pragma("unroll") for (int m = 0; m < 4; ++m) _Pragma("unroll") for (int n = 0; n < 2; ++n) _Pragma("unroll") for (int k = 0; k < 2; ++k) \
;         acc[ai][bj][m][n] = __builtin_amdgcn_mfma_f32_16x16x32_bf16(Bt[n][k], At[m][k], acc[ai][bj][m][n], 0, 0, 0); __builtin_amdgcn_s_setprio(0); } while (0)
; #define G8_WAIT_V(n) asm volatile("s_waitcnt vmcnt(" #n ")" ::: "memory")
; #define G8_WAIT_L(n) asm volatile("s_waitcnt lgkmcnt(" #n ")" ::: "memory")
; #define G8_BAR __builtin_amdgcn_s_barrier()
; #define G8_SCHED __builtin_amdgcn_sched_barrier(0)
; template <class P>
; __device__ __forceinline__ void gemm_phase(LAS unsigned char* lds, const P& p, const int G, const int c) {
;     ...
;             G8_LDB(B0, 1, 0); G8_LDB(B1, 1, 1); G8_SCHED; G8_LDA(At, 1, 0); G8_STA(G8_SA(0, 1), a2, sg2, 1);
;             G8_WAIT_V(8); G8_WAIT_L(0); G8_BAR; G8_MMA(0, 0, At, B0); G8_MMA(0, 1, At, B1); G8_BAR; G8_SCHED;
;             G8_LDA(At, 1, 1); G8_STB(G8_SB(1, 0), b3, sg2, 0); G8_STB(G8_SB(1, 1), b3, sg2, 1); G8_STA(G8_SA(1, 0), a3, sg2, 0);
;             G8_WAIT_V(8); G8_WAIT_L(0); G8_BAR; G8_MMA(1, 0, At, B0); G8_MMA(1, 1, At, B1); G8_BAR; G8_SCHED;
;         }
.Lmid_155:
	s_barrier
	s_add_i32 s53, 0, 0x18000
	v_add_u32_e32 v68, s53, v152
	s_add_i32 s56, 0, 0x1c000
	ds_read_b128 v[78:81], v68
	ds_read_b128 v[118:121], v68 offset:1024
	ds_read_b128 v[176:179], v68 offset:2048
	ds_read_b128 v[180:183], v68 offset:3072
	v_add_u32_e32 v68, s56, v152
	ds_read_b128 v[184:187], v68
	ds_read_b128 v[188:191], v68 offset:1024
	ds_read_b128 v[192:195], v68 offset:2048
	ds_read_b128 v[196:199], v68 offset:3072
	s_mov_b32 m0, s34
	v_lshl_add_u64 v[68:69], v[236:237], 0, s[6:7]
	ds_read_b128 v[200:203], v175 offset:32768
	ds_read_b128 v[204:207], v175 offset:33792
	ds_read_b128 v[210:213], v175 offset:34816
	ds_read_b128 v[214:217], v175 offset:35840
	ds_read_b128 v[218:221], v175 offset:36864
	ds_read_b128 v[222:225], v175 offset:37888
	ds_read_b128 v[226:229], v175 offset:38912
	ds_read_b128 v[230:233], v175 offset:39936
	global_load_lds_dwordx4 v[68:69], off
	v_lshl_add_u64 v[68:69], v[236:237], 0, s[8:9]
	s_mov_b32 m0, s35
	s_nop 0
	global_load_lds_dwordx4 v[68:69], off
	s_waitcnt vmcnt(8)
	s_waitcnt lgkmcnt(0)
	s_barrier
	s_waitcnt lgkmcnt(0)
	v_mfma_f32_16x16x32_bf16 v[98:101], v[78:81], v[200:203], v[98:101]
	v_mfma_f32_16x16x32_bf16 v[138:141], v[176:179], v[200:203], v[138:141]
	v_mfma_f32_16x16x32_bf16 v[68:71], v[78:81], v[210:213], v[70:73]
	v_mfma_f32_16x16x32_bf16 v[114:117], v[176:179], v[210:213], v[114:117]
	v_mfma_f32_16x16x32_bf16 v[46:49], v[78:81], v[218:221], v[46:49]
	v_mfma_f32_16x16x32_bf16 v[110:113], v[176:179], v[218:221], v[110:113]
	v_mfma_f32_16x16x32_bf16 v[38:41], v[78:81], v[226:229], v[38:41]
	v_mfma_f32_16x16x32_bf16 v[130:133], v[176:179], v[226:229], v[130:133]
	v_mfma_f32_16x16x32_bf16 v[98:101], v[118:121], v[204:207], v[98:101]
	v_mfma_f32_16x16x32_bf16 v[138:141], v[180:183], v[204:207], v[138:141]
	v_mfma_f32_16x16x32_bf16 v[70:73], v[118:121], v[214:217], v[68:71]
	v_mfma_f32_16x16x32_bf16 v[114:117], v[180:183], v[214:217], v[114:117]
	v_mfma_f32_16x16x32_bf16 v[46:49], v[118:121], v[222:225], v[46:49]
	v_mfma_f32_16x16x32_bf16 v[110:113], v[180:183], v[222:225], v[110:113]
	v_mfma_f32_16x16x32_bf16 v[38:41], v[118:121], v[230:233], v[38:41]
	v_mfma_f32_16x16x32_bf16 v[130:133], v[180:183], v[230:233], v[130:133]
	v_mfma_f32_16x16x32_bf16 v[134:137], v[184:187], v[200:203], v[134:137]
	v_mfma_f32_16x16x32_bf16 v[74:77], v[192:195], v[200:203], v[74:77]
	v_mfma_f32_16x16x32_bf16 v[106:109], v[184:187], v[210:213], v[106:109]
	v_mfma_f32_16x16x32_bf16 v[50:53], v[192:195], v[210:213], v[50:53]
	v_mfma_f32_16x16x32_bf16 v[102:105], v[184:187], v[218:221], v[102:105]
	v_mfma_f32_16x16x32_bf16 v[42:45], v[192:195], v[218:221], v[42:45]
	v_mfma_f32_16x16x32_bf16 v[126:129], v[184:187], v[226:229], v[126:129]
	v_mfma_f32_16x16x32_bf16 v[34:37], v[192:195], v[226:229], v[34:37]
	v_mfma_f32_16x16x32_bf16 v[134:137], v[188:191], v[204:207], v[134:137]
	v_mfma_f32_16x16x32_bf16 v[74:77], v[196:199], v[204:207], v[74:77]
	v_mfma_f32_16x16x32_bf16 v[106:109], v[188:191], v[214:217], v[106:109]
	v_mfma_f32_16x16x32_bf16 v[50:53], v[196:199], v[214:217], v[50:53]
	v_mfma_f32_16x16x32_bf16 v[102:105], v[188:191], v[222:225], v[102:105]
	v_mfma_f32_16x16x32_bf16 v[42:45], v[196:199], v[222:225], v[42:45]
	v_mfma_f32_16x16x32_bf16 v[126:129], v[188:191], v[230:233], v[126:129]
	v_mfma_f32_16x16x32_bf16 v[34:37], v[196:199], v[230:233], v[34:37]
	s_barrier
	s_add_i32 s53, s53, s2
	v_lshl_add_u64 v[68:69], v[234:235], 0, s[12:13]
	s_mov_b32 m0, s53
	ds_read_b128 v[200:203], v175 offset:49152
	ds_read_b128 v[204:207], v175 offset:50176
	ds_read_b128 v[210:213], v175 offset:51200
	ds_read_b128 v[214:217], v175 offset:52224
	ds_read_b128 v[218:221], v175 offset:53248
	ds_read_b128 v[222:225], v175 offset:54272
	ds_read_b128 v[226:229], v175 offset:55296
	ds_read_b128 v[230:233], v175 offset:56320
	global_load_lds_dwordx4 v[68:69], off
	v_lshl_add_u64 v[68:69], v[234:235], 0, s[14:15]
	s_add_i32 m0, s53, 0x2000
	s_add_i32 s53, s56, s2
	global_load_lds_dwordx4 v[68:69], off
	v_lshl_add_u64 v[68:69], v[234:235], 0, s[22:23]
	s_mov_b32 m0, s53
	s_nop 0
	global_load_lds_dwordx4 v[68:69], off
	v_lshl_add_u64 v[68:69], v[234:235], 0, s[36:37]
	s_add_i32 m0, s53, 0x2000
	s_nop 0
	global_load_lds_dwordx4 v[68:69], off
	v_lshl_add_u64 v[68:69], v[236:237], 0, s[16:17]
	s_mov_b32 m0, s47
	s_nop 0
	global_load_lds_dwordx4 v[68:69], off
	v_lshl_add_u64 v[68:69], v[236:237], 0, s[20:21]
	s_mov_b32 m0, s48
	s_nop 0
	global_load_lds_dwordx4 v[68:69], off
	s_waitcnt vmcnt(8)
	s_waitcnt lgkmcnt(0)
	s_barrier
	s_waitcnt lgkmcnt(0)
	v_mfma_f32_16x16x32_bf16 v[30:33], v[78:81], v[200:203], v[30:33]
	v_mfma_f32_16x16x32_bf16 v[122:125], v[176:179], v[200:203], v[122:125]
	v_mfma_f32_16x16x32_bf16 v[22:25], v[78:81], v[210:213], v[22:25]
	v_mfma_f32_16x16x32_bf16 v[94:97], v[176:179], v[210:213], v[94:97]
	v_mfma_f32_16x16x32_bf16 v[14:17], v[78:81], v[218:221], v[14:17]
	v_mfma_f32_16x16x32_bf16 v[90:93], v[176:179], v[218:221], v[90:93]
	v_mfma_f32_16x16x32_bf16 v[6:9], v[78:81], v[226:229], v[6:9]
	v_mfma_f32_16x16x32_bf16 v[56:59], v[176:179], v[226:229], v[56:59]
	v_mfma_f32_16x16x32_bf16 v[30:33], v[118:121], v[204:207], v[30:33]
	v_mfma_f32_16x16x32_bf16 v[122:125], v[180:183], v[204:207], v[122:125]
	v_mfma_f32_16x16x32_bf16 v[22:25], v[118:121], v[214:217], v[22:25]
	v_mfma_f32_16x16x32_bf16 v[94:97], v[180:183], v[214:217], v[94:97]
	v_mfma_f32_16x16x32_bf16 v[14:17], v[118:121], v[222:225], v[14:17]
	v_mfma_f32_16x16x32_bf16 v[90:93], v[180:183], v[222:225], v[90:93]
	v_mfma_f32_16x16x32_bf16 v[6:9], v[118:121], v[230:233], v[6:9]
	v_mfma_f32_16x16x32_bf16 v[78:81], v[180:183], v[230:233], v[56:59]
	v_mfma_f32_16x16x32_bf16 v[56:59], v[184:187], v[200:203], v[60:63]
	v_mfma_f32_16x16x32_bf16 v[118:121], v[188:191], v[204:207], v[56:59]
	v_mfma_f32_16x16x32_bf16 v[56:59], v[184:187], v[210:213], v[86:89]
	v_mfma_f32_16x16x32_bf16 v[86:89], v[188:191], v[214:217], v[56:59]
	v_mfma_f32_16x16x32_bf16 v[56:59], v[184:187], v[218:221], v[82:85]
	v_mfma_f32_16x16x32_bf16 v[26:29], v[192:195], v[200:203], v[26:29]
	v_mfma_f32_16x16x32_bf16 v[18:21], v[192:195], v[210:213], v[18:21]
	v_mfma_f32_16x16x32_bf16 v[82:85], v[188:191], v[222:225], v[56:59]
	v_mfma_f32_16x16x32_bf16 v[10:13], v[192:195], v[218:221], v[10:13]
	v_mfma_f32_16x16x32_bf16 v[56:59], v[184:187], v[226:229], v[64:67]
	v_mfma_f32_16x16x32_bf16 v[2:5], v[192:195], v[226:229], v[2:5]
	v_mfma_f32_16x16x32_bf16 v[26:29], v[196:199], v[204:207], v[26:29]
	v_mfma_f32_16x16x32_bf16 v[18:21], v[196:199], v[214:217], v[18:21]
	v_mfma_f32_16x16x32_bf16 v[10:13], v[196:199], v[222:225], v[10:13]
	v_mfma_f32_16x16x32_bf16 v[66:69], v[188:191], v[230:233], v[56:59]
	v_mfma_f32_16x16x32_bf16 v[2:5], v[196:199], v[230:233], v[2:5]
	s_add_i32 s52, s52, 2
	s_add_u32 s28, s28, 0x200000
	s_addc_u32 s29, s29, 0
	s_add_u32 s84, s84, 0x820000
	s_addc_u32 s85, s85, 0
	s_cmp_gt_u32 s52, 13
	s_cbranch_scc0 .LBB0_155
	s_barrier
	s_and_b64 vcc, exec, s[38:39]
	s_cbranch_vccz .LBB0_158
	s_barrier

; #define G8_STA(bufoff, ptr, sg, h) G8_STAGE1(bufoff, (ptr) + (h) * ((sg) ? hA1 : hA0), ((sg) ? voffA1 : voffA0), ((sg) ? r64A1 : r64A0))
; #define G8_STB(bufoff, ptr, sg, h) G8_STAGE1(bufoff, (ptr) + (h) * ((sg) ? hB1 : hB0), ((sg) ? voffB1 : voffB0), ((sg) ? r64B1 : r64B0))
; #define G8_LDA(dst, b, h) do { _Pragma("unroll") for (int m = 0; m < 4; ++m) _Pragma("unroll") for (int k = 0; k < 2; ++k) dst[m][k] = *(const LAS bf16x8*)(lds + G8_SA(b, h) + aoff + m * 2048 + k * 1024); } while (0)
; #define G8_LDB(dst, b, h) do { _Pragma("unroll") for (int n = 0; n < 2; ++n) _Pragma("unroll") for (int k = 0; k < 2; ++k) dst[n][k] = *(const LAS bf16x8*)(lds + G8_SB(b, h) + boff + n * 2048 + k * 1024); } while (0)
; #define G8_MMA(ai, bj, At, Bt) do { __builtin_amdgcn_s_setprio(1); _Pragma("unroll") for (int m = 0; m < 4; ++m) _Pragma("unroll") for (int n = 0; n < 2; ++n) _Pragma("unroll") for (int k = 0; k < 2; ++k) \
;         acc[ai][bj][m][n] = __builtin_amdgcn_mfma_f32_16x16x32_bf16(Bt[n][k], At[m][k], acc[ai][bj][m][n], 0, 0, 0); __builtin_amdgcn_s_setprio(0); } while (0)
; #define G8_BAR __builtin_amdgcn_s_barrier()
; template <class P>
; __device__ __forceinline__ void gemm_phase(LAS unsigned char* lds, const P& p, const int G, const int c) {
;     ...
;         for (int t = 0; t < nt; t += 2) {
;             const bool last = (t == nt - 2);
;             const bool sg1 = (NS > 1) && (t + 1 >= nt0);
;             const bool sg2 = (NS > 1) && !last && (t + 2 >= nt0);
;             const char* a1 = sg1 ? cA1 + (long)(t + 1 - nt0) * ksA1 : cA0 + (long)(t + 1) * ksA0;
;             const char* a2 = last ? nA0 : (sg2 ? cA1 + (long)(t + 2 - nt0) * ksA1 : cA0 + (long)(t + 2) * ksA0);
;             const char* b2 = last ? nB0 : (sg2 ? cB1 + (long)(t + 2 - nt0) * ksB1 : cB0 + (long)(t + 2) * ksB0);
;             const char* a3 = a2 + (sg2 ? ksA1 : ksA0); const char* b3 = b2 + (sg2 ? ksB1 : ksB0);
;             G8_LDB(B0, 0, 0); G8_LDB(B1, 0, 1); G8_SCHED; G8_LDA(At, 0, 0); G8_STA(G8_SA(1, 1), a1, sg1, 1);
;             G8_WAIT_V(8); G8_WAIT_L(0); G8_BAR; G8_MMA(0, 0, At, B0); G8_MMA(0, 1, At, B1); G8_BAR; G8_SCHED;
;             G8_LDA(At, 0, 1); G8_STB(G8_SB(0, 0), b2, sg2, 0); G8_STB(G8_SB(0, 1), b2, sg2, 1); G8_STA(G8_SA(0, 0), a2, sg2, 0);
;             G8_WAIT_V(8); G8_WAIT_L(0); G8_BAR; G8_MMA(1, 0, At, B0); G8_MMA(1, 1, At, B1); G8_BAR; G8_SCHED;
.LBB0_277:
	s_barrier
	v_add_u32_e32 v144, s52, v1
	ds_read_b128 v[132:135], v144
	ds_read_b128 v[136:139], v144 offset:1024
	ds_read_b128 v[140:143], v144 offset:2048
	ds_read_b128 v[176:179], v144 offset:3072
	v_add_u32_e32 v144, s53, v1
	ds_read_b128 v[180:183], v144
	ds_read_b128 v[184:187], v144 offset:1024
	ds_read_b128 v[188:191], v144 offset:2048
	ds_read_b128 v[192:195], v144 offset:3072
	s_add_i32 s57, s57, 2
	s_and_b64 s[30:31], exec, s[30:31]
	s_cselect_b32 s31, s7, s49
	s_cselect_b32 s30, s18, s19
	v_lshl_add_u64 v[144:145], v[130:131], 0, s[76:77]
	s_mov_b64 s[64:65], 0x414000
	v_lshl_add_u64 v[230:231], v[144:145], 0, s[64:65]
	s_add_i32 m0, s27, 0xc000
	s_mov_b64 s[64:65], 0x416000
	ds_read_b128 v[196:199], v175
	ds_read_b128 v[200:203], v175 offset:1024
	ds_read_b128 v[204:207], v175 offset:2048
	ds_read_b128 v[210:213], v175 offset:3072
	ds_read_b128 v[214:217], v175 offset:4096
	ds_read_b128 v[218:221], v175 offset:5120
	ds_read_b128 v[222:225], v175 offset:6144
	ds_read_b128 v[226:229], v175 offset:7168
	global_load_lds_dwordx4 v[230:231], off
	v_lshl_add_u64 v[144:145], v[144:145], 0, s[64:65]
	s_add_i32 m0, s27, 0xe000
	s_nop 0
	global_load_lds_dwordx4 v[144:145], off
	s_waitcnt vmcnt(8)
	s_waitcnt lgkmcnt(0)
	s_barrier
	s_waitcnt lgkmcnt(0)
	v_mfma_f32_16x16x32_bf16 v[126:129], v[132:135], v[196:199], v[126:129]
	v_mfma_f32_16x16x32_bf16 v[122:125], v[140:143], v[196:199], v[122:125]
	v_mfma_f32_16x16x32_bf16 v[118:121], v[132:135], v[204:207], v[118:121]
	v_mfma_f32_16x16x32_bf16 v[114:117], v[140:143], v[204:207], v[114:117]
	v_mfma_f32_16x16x32_bf16 v[106:109], v[132:135], v[214:217], v[106:109]
	v_mfma_f32_16x16x32_bf16 v[98:101], v[140:143], v[214:217], v[98:101]
	v_mfma_f32_16x16x32_bf16 v[94:97], v[132:135], v[222:225], v[94:97]
	v_mfma_f32_16x16x32_bf16 v[86:89], v[140:143], v[222:225], v[86:89]
	v_mfma_f32_16x16x32_bf16 v[126:129], v[136:139], v[200:203], v[126:129]
	v_mfma_f32_16x16x32_bf16 v[122:125], v[176:179], v[200:203], v[122:125]
	v_mfma_f32_16x16x32_bf16 v[118:121], v[136:139], v[210:213], v[118:121]
	v_mfma_f32_16x16x32_bf16 v[114:117], v[176:179], v[210:213], v[114:117]
	v_mfma_f32_16x16x32_bf16 v[106:109], v[136:139], v[218:221], v[106:109]
	v_mfma_f32_16x16x32_bf16 v[98:101], v[176:179], v[218:221], v[98:101]
	v_mfma_f32_16x16x32_bf16 v[94:97], v[136:139], v[226:229], v[94:97]
	v_mfma_f32_16x16x32_bf16 v[86:89], v[176:179], v[226:229], v[86:89]
	v_mfma_f32_16x16x32_bf16 v[110:113], v[180:183], v[196:199], v[110:113]
	v_mfma_f32_16x16x32_bf16 v[102:105], v[188:191], v[196:199], v[102:105]
	v_mfma_f32_16x16x32_bf16 v[90:93], v[180:183], v[204:207], v[90:93]
	v_mfma_f32_16x16x32_bf16 v[82:85], v[188:191], v[204:207], v[82:85]
	v_mfma_f32_16x16x32_bf16 v[78:81], v[180:183], v[214:217], v[78:81]
	v_mfma_f32_16x16x32_bf16 v[74:77], v[188:191], v[214:217], v[74:77]
	v_mfma_f32_16x16x32_bf16 v[70:73], v[180:183], v[222:225], v[70:73]
	v_mfma_f32_16x16x32_bf16 v[66:69], v[188:191], v[222:225], v[66:69]
	v_mfma_f32_16x16x32_bf16 v[110:113], v[184:187], v[200:203], v[110:113]
	v_mfma_f32_16x16x32_bf16 v[102:105], v[192:195], v[200:203], v[102:105]
	v_mfma_f32_16x16x32_bf16 v[90:93], v[184:187], v[210:213], v[90:93]
	v_mfma_f32_16x16x32_bf16 v[82:85], v[192:195], v[210:213], v[82:85]
	v_mfma_f32_16x16x32_bf16 v[78:81], v[184:187], v[218:221], v[78:81]
	v_mfma_f32_16x16x32_bf16 v[74:77], v[192:195], v[218:221], v[74:77]
	v_mfma_f32_16x16x32_bf16 v[70:73], v[184:187], v[226:229], v[70:73]
	v_mfma_f32_16x16x32_bf16 v[66:69], v[192:195], v[226:229], v[66:69]
	s_barrier
	v_lshl_add_u64 v[144:145], s[30:31], 0, v[148:149]
	s_add_i32 s30, s52, s26
	s_mov_b32 m0, s30
	ds_read_b128 v[196:199], v175 offset:16384
	ds_read_b128 v[200:203], v175 offset:17408
	ds_read_b128 v[204:207], v175 offset:18432
	ds_read_b128 v[210:213], v175 offset:19456
	ds_read_b128 v[214:217], v175 offset:20480
	ds_read_b128 v[218:221], v175 offset:21504
	ds_read_b128 v[222:225], v175 offset:22528
	ds_read_b128 v[226:229], v175 offset:23552
	global_load_lds_dwordx4 v[144:145], off
	v_lshl_add_u64 v[230:231], v[144:145], 0, s[10:11]
	s_add_i32 m0, s30, 0x2000
	s_add_i32 s30, s53, s26
	global_load_lds_dwordx4 v[230:231], off
	v_lshl_add_u64 v[230:231], v[144:145], 0, s[12:13]
	s_mov_b32 m0, s30
	s_nop 0
	global_load_lds_dwordx4 v[230:231], off
	v_lshl_add_u64 v[230:231], v[144:145], 0, s[14:15]
	s_add_i32 m0, s30, 0x2000
	s_nop 0
	global_load_lds_dwordx4 v[230:231], off
	v_lshl_add_u64 v[230:231], s[28:29], 0, v[150:151]
	s_mov_b32 m0, s27
	v_lshl_add_u64 v[232:233], v[230:231], 0, s[10:11]
	global_load_lds_dwordx4 v[230:231], off
	s_mov_b32 m0, s33
	s_nop 0
	global_load_lds_dwordx4 v[232:233], off
	s_waitcnt vmcnt(8)
	s_waitcnt lgkmcnt(0)
	s_barrier
	s_waitcnt lgkmcnt(0)
	v_mfma_f32_16x16x32_bf16 v[62:65], v[132:135], v[196:199], v[62:65]
	v_mfma_f32_16x16x32_bf16 v[58:61], v[140:143], v[196:199], v[58:61]
	v_mfma_f32_16x16x32_bf16 v[54:57], v[132:135], v[204:207], v[54:57]
	v_mfma_f32_16x16x32_bf16 v[50:53], v[140:143], v[204:207], v[50:53]
	v_mfma_f32_16x16x32_bf16 v[46:49], v[132:135], v[214:217], v[46:49]
	v_mfma_f32_16x16x32_bf16 v[38:41], v[140:143], v[214:217], v[38:41]
	v_mfma_f32_16x16x32_bf16 v[30:33], v[132:135], v[222:225], v[30:33]
	v_mfma_f32_16x16x32_bf16 v[22:25], v[140:143], v[222:225], v[22:25]
	v_mfma_f32_16x16x32_bf16 v[62:65], v[136:139], v[200:203], v[62:65]
	v_mfma_f32_16x16x32_bf16 v[58:61], v[176:179], v[200:203], v[58:61]
	v_mfma_f32_16x16x32_bf16 v[54:57], v[136:139], v[210:213], v[54:57]
	v_mfma_f32_16x16x32_bf16 v[50:53], v[176:179], v[210:213], v[50:53]
	v_mfma_f32_16x16x32_bf16 v[46:49], v[136:139], v[218:221], v[46:49]
	v_mfma_f32_16x16x32_bf16 v[38:41], v[176:179], v[218:221], v[38:41]
	v_mfma_f32_16x16x32_bf16 v[30:33], v[136:139], v[226:229], v[30:33]
	v_mfma_f32_16x16x32_bf16 v[22:25], v[176:179], v[226:229], v[22:25]
	v_mfma_f32_16x16x32_bf16 v[42:45], v[180:183], v[196:199], v[42:45]
	v_mfma_f32_16x16x32_bf16 v[34:37], v[188:191], v[196:199], v[34:37]
	v_mfma_f32_16x16x32_bf16 v[26:29], v[180:183], v[204:207], v[26:29]
	v_mfma_f32_16x16x32_bf16 v[18:21], v[188:191], v[204:207], v[18:21]
	v_mfma_f32_16x16x32_bf16 v[14:17], v[180:183], v[214:217], v[14:17]
	v_mfma_f32_16x16x32_bf16 v[10:13], v[188:191], v[214:217], v[10:13]
	v_mfma_f32_16x16x32_bf16 v[6:9], v[180:183], v[222:225], v[6:9]
	v_mfma_f32_16x16x32_bf16 v[2:5], v[188:191], v[222:225], v[2:5]
	v_mfma_f32_16x16x32_bf16 v[42:45], v[184:187], v[200:203], v[42:45]
	v_mfma_f32_16x16x32_bf16 v[34:37], v[192:195], v[200:203], v[34:37]
	v_mfma_f32_16x16x32_bf16 v[26:29], v[184:187], v[210:213], v[26:29]
	v_mfma_f32_16x16x32_bf16 v[18:21], v[192:195], v[210:213], v[18:21]
	v_mfma_f32_16x16x32_bf16 v[14:17], v[184:187], v[218:221], v[14:17]
	v_mfma_f32_16x16x32_bf16 v[10:13], v[192:195], v[218:221], v[10:13]
	v_mfma_f32_16x16x32_bf16 v[6:9], v[184:187], v[226:229], v[6:9]
	v_mfma_f32_16x16x32_bf16 v[2:5], v[192:195], v[226:229], v[2:5]
; #define G8_STA(bufoff, ptr, sg, h) G8_STAGE1(bufoff, (ptr) + (h) * ((sg) ? hA1 : hA0), ((sg) ? voffA1 : voffA0), ((sg) ? r64A1 : r64A0))
; #define G8_STB(bufoff, ptr, sg, h) G8_STAGE1(bufoff, (ptr) + (h) * ((sg) ? hB1 : hB0), ((sg) ? voffB1 : voffB0), ((sg) ? r64B1 : r64B0))
; #define G8_LDA(dst, b, h) do { _Pragma("unroll") for (int m = 0; m < 4; ++m) _Pragma("unroll") for (int k = 0; k < 2; ++k) dst[m][k] = *(const LAS bf16x8*)(lds + G8_SA(b, h) + aoff + m * 2048 + k * 1024); } while (0)
; #define G8_LDB(dst, b, h) do { _Pragma("unroll") for (int n = 0; n < 2; ++n) _Pragma("unroll") for (int k = 0; k < 2; ++k) dst[n][k] = *(const LAS bf16x8*)(lds + G8_SB(b, h) + boff + n * 2048 + k * 1024); } while (0)
; #define G8_MMA(ai, bj, At, Bt) do { __builtin_amdgcn_s_setprio(1); _Pragma("unroll") for (int m = 0; m < 4; ++m) _Pragma("unroll") for (int n = 0; n < 2; ++n) _Pragma("unroll") for (int k = 0; k < 2; ++k) \
;         acc[ai][bj][m][n] = __builtin_amdgcn_mfma_f32_16x16x32_bf16(Bt[n][k], At[m][k], acc[ai][bj][m][n], 0, 0, 0); __builtin_amdgcn_s_setprio(0); } while (0)
; #define G8_WAIT_V(n) asm volatile("s_waitcnt vmcnt(" #n ")" ::: "memory")
; #define G8_WAIT_L(n) asm volatile("s_waitcnt lgkmcnt(" #n ")" ::: "memory")
; #define G8_BAR __builtin_amdgcn_s_barrier()
; #define G8_SCHED __builtin_amdgcn_sched_barrier(0)
; template <class P>
; __device__ __forceinline__ void gemm_phase(LAS unsigned char* lds, const P& p, const int G, const int c) {
;     ...
;             G8_LDB(B0, 1, 0); G8_LDB(B1, 1, 1); G8_SCHED; G8_LDA(At, 1, 0); G8_STA(G8_SA(0, 1), a2, sg2, 1);
;             G8_WAIT_V(8); G8_WAIT_L(0); G8_BAR; G8_MMA(0, 0, At, B0); G8_MMA(0, 1, At, B1); G8_BAR; G8_SCHED;
;             G8_LDA(At, 1, 1); G8_STB(G8_SB(1, 0), b3, sg2, 0); G8_STB(G8_SB(1, 1), b3, sg2, 1); G8_STA(G8_SA(1, 0), a3, sg2, 0);
;             G8_WAIT_V(8); G8_WAIT_L(0); G8_BAR; G8_MMA(1, 0, At, B0); G8_MMA(1, 1, At, B1); G8_BAR; G8_SCHED;
;         }
.Lmid_277:
	s_barrier
	s_add_i32 s28, 0, 0x18000
	s_add_i32 s29, 0, 0x1c000
	v_add_u32_e32 v176, s28, v1
	v_add_u32_e32 v192, s29, v1
	ds_read_b128 v[132:135], v176
	ds_read_b128 v[136:139], v176 offset:1024
	ds_read_b128 v[140:143], v176 offset:2048
	ds_read_b128 v[176:179], v176 offset:3072
	ds_read_b128 v[180:183], v192
	ds_read_b128 v[184:187], v192 offset:1024
	ds_read_b128 v[188:191], v192 offset:2048
	ds_read_b128 v[192:195], v192 offset:3072
	s_mov_b32 m0, s34
	v_lshl_add_u64 v[232:233], v[230:231], 0, s[12:13]
	ds_read_b128 v[196:199], v175 offset:32768
	ds_read_b128 v[200:203], v175 offset:33792
	ds_read_b128 v[204:207], v175 offset:34816
	ds_read_b128 v[210:213], v175 offset:35840
	ds_read_b128 v[214:217], v175 offset:36864
	ds_read_b128 v[218:221], v175 offset:37888
	ds_read_b128 v[222:225], v175 offset:38912
	ds_read_b128 v[226:229], v175 offset:39936
	global_load_lds_dwordx4 v[232:233], off
	v_lshl_add_u64 v[232:233], v[230:231], 0, s[14:15]
	s_mov_b32 m0, s35
	s_nop 0
	global_load_lds_dwordx4 v[232:233], off
	s_waitcnt vmcnt(8)
	s_waitcnt lgkmcnt(0)
	s_barrier
	s_waitcnt lgkmcnt(0)
	v_mfma_f32_16x16x32_bf16 v[126:129], v[132:135], v[196:199], v[126:129]
	v_mfma_f32_16x16x32_bf16 v[122:125], v[140:143], v[196:199], v[122:125]
	v_mfma_f32_16x16x32_bf16 v[118:121], v[132:135], v[204:207], v[118:121]
	v_mfma_f32_16x16x32_bf16 v[114:117], v[140:143], v[204:207], v[114:117]
	v_mfma_f32_16x16x32_bf16 v[106:109], v[132:135], v[214:217], v[106:109]
	v_mfma_f32_16x16x32_bf16 v[98:101], v[140:143], v[214:217], v[98:101]
	v_mfma_f32_16x16x32_bf16 v[94:97], v[132:135], v[222:225], v[94:97]
	v_mfma_f32_16x16x32_bf16 v[86:89], v[140:143], v[222:225], v[86:89]
	v_mfma_f32_16x16x32_bf16 v[126:129], v[136:139], v[200:203], v[126:129]
	v_mfma_f32_16x16x32_bf16 v[122:125], v[176:179], v[200:203], v[122:125]
	v_mfma_f32_16x16x32_bf16 v[118:121], v[136:139], v[210:213], v[118:121]
	v_mfma_f32_16x16x32_bf16 v[114:117], v[176:179], v[210:213], v[114:117]
	v_mfma_f32_16x16x32_bf16 v[106:109], v[136:139], v[218:221], v[106:109]
	v_mfma_f32_16x16x32_bf16 v[98:101], v[176:179], v[218:221], v[98:101]
	v_mfma_f32_16x16x32_bf16 v[94:97], v[136:139], v[226:229], v[94:97]
	v_mfma_f32_16x16x32_bf16 v[86:89], v[176:179], v[226:229], v[86:89]
	v_mfma_f32_16x16x32_bf16 v[110:113], v[180:183], v[196:199], v[110:113]
	v_mfma_f32_16x16x32_bf16 v[102:105], v[188:191], v[196:199], v[102:105]
	v_mfma_f32_16x16x32_bf16 v[90:93], v[180:183], v[204:207], v[90:93]
	v_mfma_f32_16x16x32_bf16 v[82:85], v[188:191], v[204:207], v[82:85]
	v_mfma_f32_16x16x32_bf16 v[78:81], v[180:183], v[214:217], v[78:81]
	v_mfma_f32_16x16x32_bf16 v[74:77], v[188:191], v[214:217], v[74:77]
	v_mfma_f32_16x16x32_bf16 v[70:73], v[180:183], v[222:225], v[70:73]
	v_mfma_f32_16x16x32_bf16 v[66:69], v[188:191], v[222:225], v[66:69]
	v_mfma_f32_16x16x32_bf16 v[110:113], v[184:187], v[200:203], v[110:113]
	v_mfma_f32_16x16x32_bf16 v[102:105], v[192:195], v[200:203], v[102:105]
	v_mfma_f32_16x16x32_bf16 v[90:93], v[184:187], v[210:213], v[90:93]
	v_mfma_f32_16x16x32_bf16 v[82:85], v[192:195], v[210:213], v[82:85]
	v_mfma_f32_16x16x32_bf16 v[78:81], v[184:187], v[218:221], v[78:81]
	v_mfma_f32_16x16x32_bf16 v[74:77], v[192:195], v[218:221], v[74:77]
	v_mfma_f32_16x16x32_bf16 v[70:73], v[184:187], v[226:229], v[70:73]
	v_mfma_f32_16x16x32_bf16 v[66:69], v[192:195], v[226:229], v[66:69]
	s_barrier
	s_add_i32 s28, s28, s26
	v_lshl_add_u64 v[232:233], v[144:145], 0, s[20:21]
	s_mov_b32 m0, s28
	ds_read_b128 v[196:199], v175 offset:49152
	ds_read_b128 v[200:203], v175 offset:50176
	ds_read_b128 v[204:207], v175 offset:51200
	ds_read_b128 v[210:213], v175 offset:52224
	ds_read_b128 v[214:217], v175 offset:53248
	ds_read_b128 v[218:221], v175 offset:54272
	ds_read_b128 v[222:225], v175 offset:55296
	ds_read_b128 v[226:229], v175 offset:56320
	global_load_lds_dwordx4 v[232:233], off
	v_lshl_add_u64 v[232:233], v[144:145], 0, s[22:23]
	s_add_i32 m0, s28, 0x2000
	s_add_i32 s28, s29, s26
	global_load_lds_dwordx4 v[232:233], off
	v_lshl_add_u64 v[232:233], v[144:145], 0, s[40:41]
	s_mov_b32 m0, s28
	v_lshl_add_u64 v[144:145], v[144:145], 0, s[42:43]
	global_load_lds_dwordx4 v[232:233], off
	s_add_i32 m0, s28, 0x2000
	s_nop 0
	global_load_lds_dwordx4 v[144:145], off
	v_lshl_add_u64 v[144:145], v[230:231], 0, s[36:37]
	s_mov_b32 m0, s50
	s_nop 0
	global_load_lds_dwordx4 v[144:145], off
	v_lshl_add_u64 v[144:145], v[230:231], 0, s[38:39]
	s_mov_b32 m0, s51
	s_nop 0
	global_load_lds_dwordx4 v[144:145], off
	s_waitcnt vmcnt(8)
	s_waitcnt lgkmcnt(0)
	s_barrier
	s_waitcnt lgkmcnt(0)
	v_mfma_f32_16x16x32_bf16 v[62:65], v[132:135], v[196:199], v[62:65]
	v_mfma_f32_16x16x32_bf16 v[58:61], v[140:143], v[196:199], v[58:61]
	v_mfma_f32_16x16x32_bf16 v[54:57], v[132:135], v[204:207], v[54:57]
	v_mfma_f32_16x16x32_bf16 v[50:53], v[140:143], v[204:207], v[50:53]
	v_mfma_f32_16x16x32_bf16 v[46:49], v[132:135], v[214:217], v[46:49]
	v_mfma_f32_16x16x32_bf16 v[38:41], v[140:143], v[214:217], v[38:41]
	v_mfma_f32_16x16x32_bf16 v[30:33], v[132:135], v[222:225], v[30:33]
	v_mfma_f32_16x16x32_bf16 v[22:25], v[140:143], v[222:225], v[22:25]
	v_mfma_f32_16x16x32_bf16 v[62:65], v[136:139], v[200:203], v[62:65]
	v_mfma_f32_16x16x32_bf16 v[58:61], v[176:179], v[200:203], v[58:61]
	v_mfma_f32_16x16x32_bf16 v[54:57], v[136:139], v[210:213], v[54:57]
	v_mfma_f32_16x16x32_bf16 v[50:53], v[176:179], v[210:213], v[50:53]
	v_mfma_f32_16x16x32_bf16 v[46:49], v[136:139], v[218:221], v[46:49]
	v_mfma_f32_16x16x32_bf16 v[38:41], v[176:179], v[218:221], v[38:41]
	v_mfma_f32_16x16x32_bf16 v[30:33], v[136:139], v[226:229], v[30:33]
	v_mfma_f32_16x16x32_bf16 v[22:25], v[176:179], v[226:229], v[22:25]
	v_mfma_f32_16x16x32_bf16 v[42:45], v[180:183], v[196:199], v[42:45]
	v_mfma_f32_16x16x32_bf16 v[34:37], v[188:191], v[196:199], v[34:37]
	v_mfma_f32_16x16x32_bf16 v[26:29], v[180:183], v[204:207], v[26:29]
	v_mfma_f32_16x16x32_bf16 v[18:21], v[188:191], v[204:207], v[18:21]
	v_mfma_f32_16x16x32_bf16 v[14:17], v[180:183], v[214:217], v[14:17]
	v_mfma_f32_16x16x32_bf16 v[10:13], v[188:191], v[214:217], v[10:13]
	v_mfma_f32_16x16x32_bf16 v[6:9], v[180:183], v[222:225], v[6:9]
	v_mfma_f32_16x16x32_bf16 v[2:5], v[188:191], v[222:225], v[2:5]
	v_mfma_f32_16x16x32_bf16 v[42:45], v[184:187], v[200:203], v[42:45]
	v_mfma_f32_16x16x32_bf16 v[34:37], v[192:195], v[200:203], v[34:37]
	v_mfma_f32_16x16x32_bf16 v[26:29], v[184:187], v[210:213], v[26:29]
	v_mfma_f32_16x16x32_bf16 v[18:21], v[192:195], v[210:213], v[18:21]
	v_mfma_f32_16x16x32_bf16 v[14:17], v[184:187], v[218:221], v[14:17]
	v_mfma_f32_16x16x32_bf16 v[10:13], v[192:195], v[218:221], v[10:13]
	v_mfma_f32_16x16x32_bf16 v[6:9], v[184:187], v[226:229], v[6:9]
	v_mfma_f32_16x16x32_bf16 v[2:5], v[192:195], v[226:229], v[2:5]
	s_add_u32 s19, s19, 0x40000
	s_addc_u32 s49, s49, 0
	s_add_u32 s76, s76, 0x820000
	s_addc_u32 s77, s77, 0
	s_cmp_ge_u32 s57, s5
	s_cbranch_scc1 .Lrotx_277

; #define G8_MMA(ai, bj, At, Bt) do { __builtin_amdgcn_s_setprio(1); _Pragma("unroll") for (int m = 0; m < 4; ++m) _Pragma("unroll") for (int n = 0; n < 2; ++n) _Pragma("unroll") for (int k = 0; k < 2; ++k) \
;         acc[ai][bj][m][n] = __builtin_amdgcn_mfma_f32_16x16x32_bf16(Bt[n][k], At[m][k], acc[ai][bj][m][n], 0, 0, 0); __builtin_amdgcn_s_setprio(0); } while (0)
; #define G8_WAIT_V(n) asm volatile("s_waitcnt vmcnt(" #n ")" ::: "memory")
; #define G8_WAIT_L(n) asm volatile("s_waitcnt lgkmcnt(" #n ")" ::: "memory")
; #define G8_BAR __builtin_amdgcn_s_barrier()
; #define G8_SCHED __builtin_amdgcn_sched_barrier(0)
; template <class P>
; __device__ __forceinline__ void gemm_phase(LAS unsigned char* lds, const P& p, const int G, const int c) {
;     ...
;             G8_WAIT_V(8); G8_WAIT_L(0); G8_BAR; G8_MMA(1, 0, At, B0); G8_MMA(1, 1, At, B1); G8_BAR; G8_SCHED;
;         }
;         if (wr == 0) G8_BAR;
.Lrotx_277:
	s_barrier
	s_branch .LBB0_282

; #define G8_STA(bufoff, ptr, sg, h) G8_STAGE1(bufoff, (ptr) + (h) * ((sg) ? hA1 : hA0), ((sg) ? voffA1 : voffA0), ((sg) ? r64A1 : r64A0))
; #define G8_STB(bufoff, ptr, sg, h) G8_STAGE1(bufoff, (ptr) + (h) * ((sg) ? hB1 : hB0), ((sg) ? voffB1 : voffB0), ((sg) ? r64B1 : r64B0))
; #define G8_LDA(dst, b, h) do { _Pragma("unroll") for (int m = 0; m < 4; ++m) _Pragma("unroll") for (int k = 0; k < 2; ++k) dst[m][k] = *(const LAS bf16x8*)(lds + G8_SA(b, h) + aoff + m * 2048 + k * 1024); } while (0)
; #define G8_LDB(dst, b, h) do { _Pragma("unroll") for (int n = 0; n < 2; ++n) _Pragma("unroll") for (int k = 0; k < 2; ++k) dst[n][k] = *(const LAS bf16x8*)(lds + G8_SB(b, h) + boff + n * 2048 + k * 1024); } while (0)
; #define G8_MMA(ai, bj, At, Bt) do { __builtin_amdgcn_s_setprio(1); _Pragma("unroll") for (int m = 0; m < 4; ++m) _Pragma("unroll") for (int n = 0; n < 2; ++n) _Pragma("unroll") for (int k = 0; k < 2; ++k) \
;         acc[ai][bj][m][n] = __builtin_amdgcn_mfma_f32_16x16x32_bf16(Bt[n][k], At[m][k], acc[ai][bj][m][n], 0, 0, 0); __builtin_amdgcn_s_setprio(0); } while (0)
; #define G8_BAR __builtin_amdgcn_s_barrier()
; template <class P>
; __device__ __forceinline__ void gemm_phase(LAS unsigned char* lds, const P& p, const int G, const int c) {
;     ...
;         for (int t = 0; t < nt; t += 2) {
;             const bool last = (t == nt - 2);
;             const bool sg1 = (NS > 1) && (t + 1 >= nt0);
;             const bool sg2 = (NS > 1) && !last && (t + 2 >= nt0);
;             const char* a1 = sg1 ? cA1 + (long)(t + 1 - nt0) * ksA1 : cA0 + (long)(t + 1) * ksA0;
;             const char* a2 = last ? nA0 : (sg2 ? cA1 + (long)(t + 2 - nt0) * ksA1 : cA0 + (long)(t + 2) * ksA0);
;             const char* b2 = last ? nB0 : (sg2 ? cB1 + (long)(t + 2 - nt0) * ksB1 : cB0 + (long)(t + 2) * ksB0);
;             const char* a3 = a2 + (sg2 ? ksA1 : ksA0); const char* b3 = b2 + (sg2 ? ksB1 : ksB0);
;             G8_LDB(B0, 0, 0); G8_LDB(B1, 0, 1); G8_SCHED; G8_LDA(At, 0, 0); G8_STA(G8_SA(1, 1), a1, sg1, 1);
;             G8_WAIT_V(8); G8_WAIT_L(0); G8_BAR; G8_MMA(0, 0, At, B0); G8_MMA(0, 1, At, B1); G8_BAR; G8_SCHED;
;             G8_LDA(At, 0, 1); G8_STB(G8_SB(0, 0), b2, sg2, 0); G8_STB(G8_SB(0, 1), b2, sg2, 1); G8_STA(G8_SA(0, 0), a2, sg2, 0);
;             G8_WAIT_V(8); G8_WAIT_L(0); G8_BAR; G8_MMA(1, 0, At, B0); G8_MMA(1, 1, At, B1); G8_BAR; G8_SCHED;
.LBB0_410:
	s_barrier
	v_add_u32_e32 v130, s65, v137
	ds_read_b128 v[142:145], v130
	ds_read_b128 v[146:149], v130 offset:1024
	ds_read_b128 v[162:165], v130 offset:2048
	ds_read_b128 v[166:169], v130 offset:3072
	v_add_u32_e32 v130, s66, v137
	ds_read_b128 v[170:173], v130
	ds_read_b128 v[174:177], v130 offset:1024
	ds_read_b128 v[178:181], v130 offset:2048
	ds_read_b128 v[182:185], v130 offset:3072
	s_add_i32 s74, s74, 2
	s_and_b64 s[30:31], exec, s[30:31]
	s_cselect_b32 s31, s7, s53
	s_cselect_b32 s30, s18, s19
	v_lshl_add_u64 v[206:207], v[140:141], 0, s[70:71]
	v_lshl_add_u64 v[222:223], v[206:207], 0, s[76:77]
	s_add_i32 m0, s27, 0xc000
	ds_read_b128 v[186:189], v158
	ds_read_b128 v[190:193], v158 offset:1024
	ds_read_b128 v[194:197], v158 offset:2048
	ds_read_b128 v[198:201], v158 offset:3072
	ds_read_b128 v[202:205], v158 offset:4096
	ds_read_b128 v[210:213], v158 offset:5120
	ds_read_b128 v[214:217], v158 offset:6144
	ds_read_b128 v[218:221], v158 offset:7168
	global_load_lds_dwordx4 v[222:223], off
	v_lshl_add_u64 v[206:207], v[206:207], 0, s[48:49]
	s_add_i32 m0, s27, 0xe000
	s_nop 0
	global_load_lds_dwordx4 v[206:207], off
	s_waitcnt vmcnt(8)
	s_waitcnt lgkmcnt(0)
	s_barrier
	s_waitcnt lgkmcnt(0)
	v_mfma_f32_16x16x32_bf16 v[126:129], v[142:145], v[186:189], v[126:129]
	v_mfma_f32_16x16x32_bf16 v[122:125], v[162:165], v[186:189], v[122:125]
	v_mfma_f32_16x16x32_bf16 v[110:113], v[142:145], v[194:197], v[110:113]
	v_mfma_f32_16x16x32_bf16 v[106:109], v[162:165], v[194:197], v[106:109]
	v_mfma_f32_16x16x32_bf16 v[94:97], v[142:145], v[202:205], v[94:97]
	v_mfma_f32_16x16x32_bf16 v[90:93], v[162:165], v[202:205], v[90:93]
	v_mfma_f32_16x16x32_bf16 v[78:81], v[142:145], v[214:217], v[78:81]
	v_mfma_f32_16x16x32_bf16 v[74:77], v[162:165], v[214:217], v[74:77]
	v_mfma_f32_16x16x32_bf16 v[126:129], v[146:149], v[190:193], v[126:129]
	v_mfma_f32_16x16x32_bf16 v[122:125], v[166:169], v[190:193], v[122:125]
	v_mfma_f32_16x16x32_bf16 v[110:113], v[146:149], v[198:201], v[110:113]
	v_mfma_f32_16x16x32_bf16 v[106:109], v[166:169], v[198:201], v[106:109]
	v_mfma_f32_16x16x32_bf16 v[94:97], v[146:149], v[210:213], v[94:97]
	v_mfma_f32_16x16x32_bf16 v[90:93], v[166:169], v[210:213], v[90:93]
	v_mfma_f32_16x16x32_bf16 v[78:81], v[146:149], v[218:221], v[78:81]
	v_mfma_f32_16x16x32_bf16 v[74:77], v[166:169], v[218:221], v[74:77]
	v_mfma_f32_16x16x32_bf16 v[118:121], v[170:173], v[186:189], v[118:121]
	v_mfma_f32_16x16x32_bf16 v[114:117], v[178:181], v[186:189], v[114:117]
	v_mfma_f32_16x16x32_bf16 v[102:105], v[170:173], v[194:197], v[102:105]
	v_mfma_f32_16x16x32_bf16 v[98:101], v[178:181], v[194:197], v[98:101]
	v_mfma_f32_16x16x32_bf16 v[86:89], v[170:173], v[202:205], v[86:89]
	v_mfma_f32_16x16x32_bf16 v[82:85], v[178:181], v[202:205], v[82:85]
	v_mfma_f32_16x16x32_bf16 v[70:73], v[170:173], v[214:217], v[70:73]
	v_mfma_f32_16x16x32_bf16 v[66:69], v[178:181], v[214:217], v[66:69]
	v_mfma_f32_16x16x32_bf16 v[118:121], v[174:177], v[190:193], v[118:121]
	v_mfma_f32_16x16x32_bf16 v[114:117], v[182:185], v[190:193], v[114:117]
	v_mfma_f32_16x16x32_bf16 v[102:105], v[174:177], v[198:201], v[102:105]
	v_mfma_f32_16x16x32_bf16 v[98:101], v[182:185], v[198:201], v[98:101]
	v_mfma_f32_16x16x32_bf16 v[86:89], v[174:177], v[210:213], v[86:89]
	v_mfma_f32_16x16x32_bf16 v[82:85], v[182:185], v[210:213], v[82:85]
	v_mfma_f32_16x16x32_bf16 v[70:73], v[174:177], v[218:221], v[70:73]
	v_mfma_f32_16x16x32_bf16 v[66:69], v[182:185], v[218:221], v[66:69]
	s_barrier
	v_lshl_add_u64 v[206:207], s[30:31], 0, v[132:133]
	s_add_i32 s30, s65, s26
	s_mov_b32 m0, s30
	ds_read_b128 v[186:189], v158 offset:16384
	ds_read_b128 v[190:193], v158 offset:17408
	ds_read_b128 v[194:197], v158 offset:18432
	ds_read_b128 v[198:201], v158 offset:19456
	ds_read_b128 v[202:205], v158 offset:20480
	ds_read_b128 v[210:213], v158 offset:21504
	ds_read_b128 v[214:217], v158 offset:22528
	ds_read_b128 v[218:221], v158 offset:23552
	global_load_lds_dwordx4 v[206:207], off
	v_lshl_add_u64 v[222:223], v[206:207], 0, s[8:9]
	s_add_i32 m0, s30, 0x2000
	s_add_i32 s30, s66, s26
	global_load_lds_dwordx4 v[222:223], off
	v_lshl_add_u64 v[222:223], v[206:207], 0, s[10:11]
	s_mov_b32 m0, s30
	s_nop 0
	global_load_lds_dwordx4 v[222:223], off
	v_lshl_add_u64 v[222:223], v[206:207], 0, s[12:13]
	s_add_i32 m0, s30, 0x2000
	s_nop 0
	global_load_lds_dwordx4 v[222:223], off
	v_lshl_add_u64 v[222:223], s[28:29], 0, v[134:135]
	s_mov_b32 m0, s27
	v_lshl_add_u64 v[224:225], v[222:223], 0, s[8:9]
	global_load_lds_dwordx4 v[222:223], off
	s_mov_b32 m0, s33
	s_nop 0
	global_load_lds_dwordx4 v[224:225], off
	s_waitcnt vmcnt(8)
	s_waitcnt lgkmcnt(0)
	s_barrier
	s_waitcnt lgkmcnt(0)
	v_mfma_f32_16x16x32_bf16 v[62:65], v[142:145], v[186:189], v[62:65]
	v_mfma_f32_16x16x32_bf16 v[58:61], v[162:165], v[186:189], v[58:61]
	v_mfma_f32_16x16x32_bf16 v[46:49], v[142:145], v[194:197], v[46:49]
	v_mfma_f32_16x16x32_bf16 v[42:45], v[162:165], v[194:197], v[42:45]
	v_mfma_f32_16x16x32_bf16 v[30:33], v[142:145], v[202:205], v[30:33]
	v_mfma_f32_16x16x32_bf16 v[26:29], v[162:165], v[202:205], v[26:29]
	v_mfma_f32_16x16x32_bf16 v[14:17], v[142:145], v[214:217], v[14:17]
	v_mfma_f32_16x16x32_bf16 v[10:13], v[162:165], v[214:217], v[10:13]
	v_mfma_f32_16x16x32_bf16 v[62:65], v[146:149], v[190:193], v[62:65]
	v_mfma_f32_16x16x32_bf16 v[58:61], v[166:169], v[190:193], v[58:61]
	v_mfma_f32_16x16x32_bf16 v[46:49], v[146:149], v[198:201], v[46:49]
	v_mfma_f32_16x16x32_bf16 v[42:45], v[166:169], v[198:201], v[42:45]
	v_mfma_f32_16x16x32_bf16 v[30:33], v[146:149], v[210:213], v[30:33]
	v_mfma_f32_16x16x32_bf16 v[26:29], v[166:169], v[210:213], v[26:29]
	v_mfma_f32_16x16x32_bf16 v[14:17], v[146:149], v[218:221], v[14:17]
	v_mfma_f32_16x16x32_bf16 v[10:13], v[166:169], v[218:221], v[10:13]
	v_mfma_f32_16x16x32_bf16 v[54:57], v[170:173], v[186:189], v[54:57]
	v_mfma_f32_16x16x32_bf16 v[50:53], v[178:181], v[186:189], v[50:53]
	v_mfma_f32_16x16x32_bf16 v[38:41], v[170:173], v[194:197], v[38:41]
	v_mfma_f32_16x16x32_bf16 v[34:37], v[178:181], v[194:197], v[34:37]
	v_mfma_f32_16x16x32_bf16 v[22:25], v[170:173], v[202:205], v[22:25]
	v_mfma_f32_16x16x32_bf16 v[18:21], v[178:181], v[202:205], v[18:21]
	v_mfma_f32_16x16x32_bf16 v[6:9], v[170:173], v[214:217], v[6:9]
	v_mfma_f32_16x16x32_bf16 v[2:5], v[178:181], v[214:217], v[2:5]
	v_mfma_f32_16x16x32_bf16 v[54:57], v[174:177], v[190:193], v[54:57]
	v_mfma_f32_16x16x32_bf16 v[50:53], v[182:185], v[190:193], v[50:53]
	v_mfma_f32_16x16x32_bf16 v[38:41], v[174:177], v[198:201], v[38:41]
	v_mfma_f32_16x16x32_bf16 v[34:37], v[182:185], v[198:201], v[34:37]
	v_mfma_f32_16x16x32_bf16 v[22:25], v[174:177], v[210:213], v[22:25]
	v_mfma_f32_16x16x32_bf16 v[18:21], v[182:185], v[210:213], v[18:21]
	v_mfma_f32_16x16x32_bf16 v[6:9], v[174:177], v[218:221], v[6:9]
	v_mfma_f32_16x16x32_bf16 v[2:5], v[182:185], v[218:221], v[2:5]
; #define G8_STA(bufoff, ptr, sg, h) G8_STAGE1(bufoff, (ptr) + (h) * ((sg) ? hA1 : hA0), ((sg) ? voffA1 : voffA0), ((sg) ? r64A1 : r64A0))
; #define G8_STB(bufoff, ptr, sg, h) G8_STAGE1(bufoff, (ptr) + (h) * ((sg) ? hB1 : hB0), ((sg) ? voffB1 : voffB0), ((sg) ? r64B1 : r64B0))
; #define G8_LDA(dst, b, h) do { _Pragma("unroll") for (int m = 0; m < 4; ++m) _Pragma("unroll") for (int k = 0; k < 2; ++k) dst[m][k] = *(const LAS bf16x8*)(lds + G8_SA(b, h) + aoff + m * 2048 + k * 1024); } while (0)
; #define G8_LDB(dst, b, h) do { _Pragma("unroll") for (int n = 0; n < 2; ++n) _Pragma("unroll") for (int k = 0; k < 2; ++k) dst[n][k] = *(const LAS bf16x8*)(lds + G8_SB(b, h) + boff + n * 2048 + k * 1024); } while (0)
; #define G8_MMA(ai, bj, At, Bt) do { __builtin_amdgcn_s_setprio(1); _Pragma("unroll") for (int m = 0; m < 4; ++m) _Pragma("unroll") for (int n = 0; n < 2; ++n) _Pragma("unroll") for (int k = 0; k < 2; ++k) \
;         acc[ai][bj][m][n] = __builtin_amdgcn_mfma_f32_16x16x32_bf16(Bt[n][k], At[m][k], acc[ai][bj][m][n], 0, 0, 0); __builtin_amdgcn_s_setprio(0); } while (0)
; #define G8_WAIT_V(n) asm volatile("s_waitcnt vmcnt(" #n ")" ::: "memory")
; #define G8_WAIT_L(n) asm volatile("s_waitcnt lgkmcnt(" #n ")" ::: "memory")
; #define G8_BAR __builtin_amdgcn_s_barrier()
; #define G8_SCHED __builtin_amdgcn_sched_barrier(0)
; template <class P>
; __device__ __forceinline__ void gemm_phase(LAS unsigned char* lds, const P& p, const int G, const int c) {
;     ...
;             G8_LDB(B0, 1, 0); G8_LDB(B1, 1, 1); G8_SCHED; G8_LDA(At, 1, 0); G8_STA(G8_SA(0, 1), a2, sg2, 1);
;             G8_WAIT_V(8); G8_WAIT_L(0); G8_BAR; G8_MMA(0, 0, At, B0); G8_MMA(0, 1, At, B1); G8_BAR; G8_SCHED;
;             G8_LDA(At, 1, 1); G8_STB(G8_SB(1, 0), b3, sg2, 0); G8_STB(G8_SB(1, 1), b3, sg2, 1); G8_STA(G8_SA(1, 0), a3, sg2, 0);
;             G8_WAIT_V(8); G8_WAIT_L(0); G8_BAR; G8_MMA(1, 0, At, B0); G8_MMA(1, 1, At, B1); G8_BAR; G8_SCHED;
;         }
.Lmid_410:
	s_barrier
	s_add_i32 s28, 0, 0x18000
	v_add_u32_e32 v130, s28, v137
	s_add_i32 s29, 0, 0x1c000
	ds_read_b128 v[142:145], v130
	ds_read_b128 v[146:149], v130 offset:1024
	ds_read_b128 v[162:165], v130 offset:2048
	ds_read_b128 v[166:169], v130 offset:3072
	v_add_u32_e32 v130, s29, v137
	ds_read_b128 v[170:173], v130
	ds_read_b128 v[174:177], v130 offset:1024
	ds_read_b128 v[178:181], v130 offset:2048
	ds_read_b128 v[182:185], v130 offset:3072
	s_mov_b32 m0, s34
	v_lshl_add_u64 v[224:225], v[222:223], 0, s[10:11]
	ds_read_b128 v[186:189], v158 offset:32768
	ds_read_b128 v[190:193], v158 offset:33792
	ds_read_b128 v[194:197], v158 offset:34816
	ds_read_b128 v[198:201], v158 offset:35840
	ds_read_b128 v[202:205], v158 offset:36864
	ds_read_b128 v[210:213], v158 offset:37888
	ds_read_b128 v[214:217], v158 offset:38912
	ds_read_b128 v[218:221], v158 offset:39936
	global_load_lds_dwordx4 v[224:225], off
	v_lshl_add_u64 v[224:225], v[222:223], 0, s[12:13]
	s_mov_b32 m0, s35
	s_nop 0
	global_load_lds_dwordx4 v[224:225], off
	s_waitcnt vmcnt(8)
	s_waitcnt lgkmcnt(0)
	s_barrier
	s_waitcnt lgkmcnt(0)
	v_mfma_f32_16x16x32_bf16 v[126:129], v[142:145], v[186:189], v[126:129]
	v_mfma_f32_16x16x32_bf16 v[122:125], v[162:165], v[186:189], v[122:125]
	v_mfma_f32_16x16x32_bf16 v[110:113], v[142:145], v[194:197], v[110:113]
	v_mfma_f32_16x16x32_bf16 v[106:109], v[162:165], v[194:197], v[106:109]
	v_mfma_f32_16x16x32_bf16 v[94:97], v[142:145], v[202:205], v[94:97]
	v_mfma_f32_16x16x32_bf16 v[90:93], v[162:165], v[202:205], v[90:93]
	v_mfma_f32_16x16x32_bf16 v[78:81], v[142:145], v[214:217], v[78:81]
	v_mfma_f32_16x16x32_bf16 v[74:77], v[162:165], v[214:217], v[74:77]
	v_mfma_f32_16x16x32_bf16 v[126:129], v[146:149], v[190:193], v[126:129]
	v_mfma_f32_16x16x32_bf16 v[122:125], v[166:169], v[190:193], v[122:125]
	v_mfma_f32_16x16x32_bf16 v[110:113], v[146:149], v[198:201], v[110:113]
	v_mfma_f32_16x16x32_bf16 v[106:109], v[166:169], v[198:201], v[106:109]
	v_mfma_f32_16x16x32_bf16 v[94:97], v[146:149], v[210:213], v[94:97]
	v_mfma_f32_16x16x32_bf16 v[90:93], v[166:169], v[210:213], v[90:93]
	v_mfma_f32_16x16x32_bf16 v[78:81], v[146:149], v[218:221], v[78:81]
	v_mfma_f32_16x16x32_bf16 v[74:77], v[166:169], v[218:221], v[74:77]
	v_mfma_f32_16x16x32_bf16 v[118:121], v[170:173], v[186:189], v[118:121]
	v_mfma_f32_16x16x32_bf16 v[114:117], v[178:181], v[186:189], v[114:117]
	v_mfma_f32_16x16x32_bf16 v[102:105], v[170:173], v[194:197], v[102:105]
	v_mfma_f32_16x16x32_bf16 v[98:101], v[178:181], v[194:197], v[98:101]
	v_mfma_f32_16x16x32_bf16 v[86:89], v[170:173], v[202:205], v[86:89]
	v_mfma_f32_16x16x32_bf16 v[82:85], v[178:181], v[202:205], v[82:85]
	v_mfma_f32_16x16x32_bf16 v[70:73], v[170:173], v[214:217], v[70:73]
	v_mfma_f32_16x16x32_bf16 v[66:69], v[178:181], v[214:217], v[66:69]
	v_mfma_f32_16x16x32_bf16 v[118:121], v[174:177], v[190:193], v[118:121]
	v_mfma_f32_16x16x32_bf16 v[114:117], v[182:185], v[190:193], v[114:117]
	v_mfma_f32_16x16x32_bf16 v[102:105], v[174:177], v[198:201], v[102:105]
	v_mfma_f32_16x16x32_bf16 v[98:101], v[182:185], v[198:201], v[98:101]
	v_mfma_f32_16x16x32_bf16 v[86:89], v[174:177], v[210:213], v[86:89]
	v_mfma_f32_16x16x32_bf16 v[82:85], v[182:185], v[210:213], v[82:85]
	v_mfma_f32_16x16x32_bf16 v[70:73], v[174:177], v[218:221], v[70:73]
	v_mfma_f32_16x16x32_bf16 v[66:69], v[182:185], v[218:221], v[66:69]
	s_barrier
	s_add_i32 s28, s28, s26
	v_lshl_add_u64 v[224:225], v[206:207], 0, s[20:21]
	s_mov_b32 m0, s28
	ds_read_b128 v[186:189], v158 offset:49152
	ds_read_b128 v[190:193], v158 offset:50176
	ds_read_b128 v[194:197], v158 offset:51200
	ds_read_b128 v[198:201], v158 offset:52224
	ds_read_b128 v[202:205], v158 offset:53248
	ds_read_b128 v[210:213], v158 offset:54272
	ds_read_b128 v[214:217], v158 offset:55296
	ds_read_b128 v[218:221], v158 offset:56320
	global_load_lds_dwordx4 v[224:225], off
	v_lshl_add_u64 v[224:225], v[206:207], 0, s[22:23]
	s_add_i32 m0, s28, 0x2000
	s_add_i32 s28, s29, s26
	global_load_lds_dwordx4 v[224:225], off
	v_lshl_add_u64 v[224:225], v[206:207], 0, s[40:41]
	s_mov_b32 m0, s28
	v_lshl_add_u64 v[206:207], v[206:207], 0, s[42:43]
	global_load_lds_dwordx4 v[224:225], off
	s_add_i32 m0, s28, 0x2000
	s_nop 0
	global_load_lds_dwordx4 v[206:207], off
	v_lshl_add_u64 v[206:207], v[222:223], 0, s[36:37]
	s_mov_b32 m0, s51
	s_nop 0
	global_load_lds_dwordx4 v[206:207], off
	v_lshl_add_u64 v[206:207], v[222:223], 0, s[38:39]
	s_mov_b32 m0, s64
	s_nop 0
	global_load_lds_dwordx4 v[206:207], off
	s_waitcnt vmcnt(8)
	s_waitcnt lgkmcnt(0)
	s_barrier
	s_waitcnt lgkmcnt(0)
	v_mfma_f32_16x16x32_bf16 v[62:65], v[142:145], v[186:189], v[62:65]
	v_mfma_f32_16x16x32_bf16 v[58:61], v[162:165], v[186:189], v[58:61]
	v_mfma_f32_16x16x32_bf16 v[46:49], v[142:145], v[194:197], v[46:49]
	v_mfma_f32_16x16x32_bf16 v[42:45], v[162:165], v[194:197], v[42:45]
	v_mfma_f32_16x16x32_bf16 v[30:33], v[142:145], v[202:205], v[30:33]
	v_mfma_f32_16x16x32_bf16 v[26:29], v[162:165], v[202:205], v[26:29]
	v_mfma_f32_16x16x32_bf16 v[14:17], v[142:145], v[214:217], v[14:17]
	v_mfma_f32_16x16x32_bf16 v[10:13], v[162:165], v[214:217], v[10:13]
	v_mfma_f32_16x16x32_bf16 v[62:65], v[146:149], v[190:193], v[62:65]
	v_mfma_f32_16x16x32_bf16 v[58:61], v[166:169], v[190:193], v[58:61]
	v_mfma_f32_16x16x32_bf16 v[46:49], v[146:149], v[198:201], v[46:49]
	v_mfma_f32_16x16x32_bf16 v[42:45], v[166:169], v[198:201], v[42:45]
	v_mfma_f32_16x16x32_bf16 v[30:33], v[146:149], v[210:213], v[30:33]
	v_mfma_f32_16x16x32_bf16 v[26:29], v[166:169], v[210:213], v[26:29]
	v_mfma_f32_16x16x32_bf16 v[14:17], v[146:149], v[218:221], v[14:17]
	v_mfma_f32_16x16x32_bf16 v[10:13], v[166:169], v[218:221], v[10:13]
	v_mfma_f32_16x16x32_bf16 v[54:57], v[170:173], v[186:189], v[54:57]
	v_mfma_f32_16x16x32_bf16 v[50:53], v[178:181], v[186:189], v[50:53]
	v_mfma_f32_16x16x32_bf16 v[38:41], v[170:173], v[194:197], v[38:41]
	v_mfma_f32_16x16x32_bf16 v[34:37], v[178:181], v[194:197], v[34:37]
	v_mfma_f32_16x16x32_bf16 v[22:25], v[170:173], v[202:205], v[22:25]
	v_mfma_f32_16x16x32_bf16 v[18:21], v[178:181], v[202:205], v[18:21]
	v_mfma_f32_16x16x32_bf16 v[6:9], v[170:173], v[214:217], v[6:9]
	v_mfma_f32_16x16x32_bf16 v[2:5], v[178:181], v[214:217], v[2:5]
	v_mfma_f32_16x16x32_bf16 v[54:57], v[174:177], v[190:193], v[54:57]
	v_mfma_f32_16x16x32_bf16 v[50:53], v[182:185], v[190:193], v[50:53]
	v_mfma_f32_16x16x32_bf16 v[38:41], v[174:177], v[198:201], v[38:41]
	v_mfma_f32_16x16x32_bf16 v[34:37], v[182:185], v[198:201], v[34:37]
	v_mfma_f32_16x16x32_bf16 v[22:25], v[174:177], v[210:213], v[22:25]
	v_mfma_f32_16x16x32_bf16 v[18:21], v[182:185], v[210:213], v[18:21]
	v_mfma_f32_16x16x32_bf16 v[6:9], v[174:177], v[218:221], v[6:9]
	v_mfma_f32_16x16x32_bf16 v[2:5], v[182:185], v[218:221], v[2:5]
	s_add_u32 s19, s19, 0x100000
	s_addc_u32 s53, s53, 0
	s_add_u32 s70, s70, 0x820000
	s_addc_u32 s71, s71, 0
	s_cmp_ge_u32 s74, s1
	s_cbranch_scc1 .Lrotx_410

; #define G8_STA(bufoff, ptr, sg, h) G8_STAGE1(bufoff, (ptr) + (h) * ((sg) ? hA1 : hA0), ((sg) ? voffA1 : voffA0), ((sg) ? r64A1 : r64A0))
; #define G8_STB(bufoff, ptr, sg, h) G8_STAGE1(bufoff, (ptr) + (h) * ((sg) ? hB1 : hB0), ((sg) ? voffB1 : voffB0), ((sg) ? r64B1 : r64B0))
; #define G8_LDA(dst, b, h) do { _Pragma("unroll") for (int m = 0; m < 4; ++m) _Pragma("unroll") for (int k = 0; k < 2; ++k) dst[m][k] = *(const LAS bf16x8*)(lds + G8_SA(b, h) + aoff + m * 2048 + k * 1024); } while (0)
; #define G8_LDB(dst, b, h) do { _Pragma("unroll") for (int n = 0; n < 2; ++n) _Pragma("unroll") for (int k = 0; k < 2; ++k) dst[n][k] = *(const LAS bf16x8*)(lds + G8_SB(b, h) + boff + n * 2048 + k * 1024); } while (0)
; #define G8_MMA(ai, bj, At, Bt) do { __builtin_amdgcn_s_setprio(1); _Pragma("unroll") for (int m = 0; m < 4; ++m) _Pragma("unroll") for (int n = 0; n < 2; ++n) _Pragma("unroll") for (int k = 0; k < 2; ++k) \
;         acc[ai][bj][m][n] = __builtin_amdgcn_mfma_f32_16x16x32_bf16(Bt[n][k], At[m][k], acc[ai][bj][m][n], 0, 0, 0); __builtin_amdgcn_s_setprio(0); } while (0)
; #define G8_BAR __builtin_amdgcn_s_barrier()
; template <class P>
; __device__ __forceinline__ void gemm_phase(LAS unsigned char* lds, const P& p, const int G, const int c) {
;     ...
;         for (int t = 0; t < nt; t += 2) {
;             const bool last = (t == nt - 2);
;             const bool sg1 = (NS > 1) && (t + 1 >= nt0);
;             const bool sg2 = (NS > 1) && !last && (t + 2 >= nt0);
;             const char* a1 = sg1 ? cA1 + (long)(t + 1 - nt0) * ksA1 : cA0 + (long)(t + 1) * ksA0;
;             const char* a2 = last ? nA0 : (sg2 ? cA1 + (long)(t + 2 - nt0) * ksA1 : cA0 + (long)(t + 2) * ksA0);
;             const char* b2 = last ? nB0 : (sg2 ? cB1 + (long)(t + 2 - nt0) * ksB1 : cB0 + (long)(t + 2) * ksB0);
;             const char* a3 = a2 + (sg2 ? ksA1 : ksA0); const char* b3 = b2 + (sg2 ? ksB1 : ksB0);
;             G8_LDB(B0, 0, 0); G8_LDB(B1, 0, 1); G8_SCHED; G8_LDA(At, 0, 0); G8_STA(G8_SA(1, 1), a1, sg1, 1);
;             G8_WAIT_V(8); G8_WAIT_L(0); G8_BAR; G8_MMA(0, 0, At, B0); G8_MMA(0, 1, At, B1); G8_BAR; G8_SCHED;
;             G8_LDA(At, 0, 1); G8_STB(G8_SB(0, 0), b2, sg2, 0); G8_STB(G8_SB(0, 1), b2, sg2, 1); G8_STA(G8_SA(0, 0), a2, sg2, 0);
;             G8_WAIT_V(8); G8_WAIT_L(0); G8_BAR; G8_MMA(1, 0, At, B0); G8_MMA(1, 1, At, B1); G8_BAR; G8_SCHED;
.LBB0_539:
	s_barrier
	s_add_u32 s6, s92, s94
	s_addc_u32 s7, s93, s95
	s_add_u32 s6, s6, 0x10000
	s_addc_u32 s7, s7, 0
	s_add_i32 s65, 0, 0x10000
	s_cmp_eq_u32 s94, 0x30000
	s_cselect_b32 s7, s18, s7
	s_cselect_b32 s6, s19, s6
	v_add_u32_e32 v130, s65, v156
	s_cselect_b32 s51, s89, s29
	s_cselect_b32 s50, s88, s28
	s_add_i32 s34, 0, 0x14000
	ds_read_b128 v[160:163], v130
	ds_read_b128 v[164:167], v130 offset:1024
	ds_read_b128 v[168:171], v130 offset:2048
	ds_read_b128 v[172:175], v130 offset:3072
	v_add_u32_e32 v130, s34, v156
	ds_read_b128 v[176:179], v130
	ds_read_b128 v[180:183], v130 offset:1024
	ds_read_b128 v[184:187], v130 offset:2048
	ds_read_b128 v[188:191], v130 offset:3072
	v_lshl_add_u64 v[226:227], v[154:155], 0, s[94:95]
	s_mov_b64 s[54:55], 0xc000
	v_lshl_add_u64 v[228:229], v[226:227], 0, s[54:55]
	s_add_i32 m0, s11, 0xc000
	s_mov_b64 s[54:55], 0xe000
	ds_read_b128 v[192:195], v158
	ds_read_b128 v[196:199], v158 offset:1024
	ds_read_b128 v[200:203], v158 offset:2048
	ds_read_b128 v[204:207], v158 offset:3072
	ds_read_b128 v[210:213], v158 offset:4096
	ds_read_b128 v[214:217], v158 offset:5120
	ds_read_b128 v[218:221], v158 offset:6144
	ds_read_b128 v[222:225], v158 offset:7168
	global_load_lds_dwordx4 v[228:229], off
	v_lshl_add_u64 v[226:227], v[226:227], 0, s[54:55]
	s_add_i32 m0, s11, 0xe000
	s_nop 0
	global_load_lds_dwordx4 v[226:227], off
	s_waitcnt vmcnt(8)
	s_waitcnt lgkmcnt(0)
	s_barrier
	s_waitcnt lgkmcnt(0)
	v_mfma_f32_16x16x32_bf16 v[126:129], v[160:163], v[192:195], v[126:129]
	v_mfma_f32_16x16x32_bf16 v[122:125], v[168:171], v[192:195], v[122:125]
	v_mfma_f32_16x16x32_bf16 v[118:121], v[160:163], v[200:203], v[118:121]
	v_mfma_f32_16x16x32_bf16 v[114:117], v[168:171], v[200:203], v[114:117]
	v_mfma_f32_16x16x32_bf16 v[102:105], v[160:163], v[210:213], v[102:105]
	v_mfma_f32_16x16x32_bf16 v[98:101], v[168:171], v[210:213], v[98:101]
	v_mfma_f32_16x16x32_bf16 v[86:89], v[160:163], v[218:221], v[86:89]
	v_mfma_f32_16x16x32_bf16 v[82:85], v[168:171], v[218:221], v[82:85]
	v_mfma_f32_16x16x32_bf16 v[126:129], v[164:167], v[196:199], v[126:129]
	v_mfma_f32_16x16x32_bf16 v[122:125], v[172:175], v[196:199], v[122:125]
	v_mfma_f32_16x16x32_bf16 v[118:121], v[164:167], v[204:207], v[118:121]
	v_mfma_f32_16x16x32_bf16 v[114:117], v[172:175], v[204:207], v[114:117]
	v_mfma_f32_16x16x32_bf16 v[102:105], v[164:167], v[214:217], v[102:105]
	v_mfma_f32_16x16x32_bf16 v[98:101], v[172:175], v[214:217], v[98:101]
	v_mfma_f32_16x16x32_bf16 v[86:89], v[164:167], v[222:225], v[86:89]
	v_mfma_f32_16x16x32_bf16 v[82:85], v[172:175], v[222:225], v[82:85]
	v_mfma_f32_16x16x32_bf16 v[110:113], v[176:179], v[192:195], v[110:113]
	v_mfma_f32_16x16x32_bf16 v[106:109], v[184:187], v[192:195], v[106:109]
	v_mfma_f32_16x16x32_bf16 v[94:97], v[176:179], v[200:203], v[94:97]
	v_mfma_f32_16x16x32_bf16 v[90:93], v[184:187], v[200:203], v[90:93]
	v_mfma_f32_16x16x32_bf16 v[78:81], v[176:179], v[210:213], v[78:81]
	v_mfma_f32_16x16x32_bf16 v[74:77], v[184:187], v[210:213], v[74:77]
	v_mfma_f32_16x16x32_bf16 v[70:73], v[176:179], v[218:221], v[70:73]
	v_mfma_f32_16x16x32_bf16 v[66:69], v[184:187], v[218:221], v[66:69]
	v_mfma_f32_16x16x32_bf16 v[110:113], v[180:183], v[196:199], v[110:113]
	v_mfma_f32_16x16x32_bf16 v[106:109], v[188:191], v[196:199], v[106:109]
	v_mfma_f32_16x16x32_bf16 v[94:97], v[180:183], v[204:207], v[94:97]
	v_mfma_f32_16x16x32_bf16 v[90:93], v[188:191], v[204:207], v[90:93]
	v_mfma_f32_16x16x32_bf16 v[78:81], v[180:183], v[214:217], v[78:81]
	v_mfma_f32_16x16x32_bf16 v[74:77], v[188:191], v[214:217], v[74:77]
	v_mfma_f32_16x16x32_bf16 v[70:73], v[180:183], v[222:225], v[70:73]
	v_mfma_f32_16x16x32_bf16 v[66:69], v[188:191], v[222:225], v[66:69]
	s_barrier
	s_add_i32 s20, s65, s10
	v_lshl_add_u64 v[226:227], s[50:51], 0, v[132:133]
	s_mov_b32 m0, s20
	ds_read_b128 v[192:195], v158 offset:16384
	ds_read_b128 v[196:199], v158 offset:17408
	ds_read_b128 v[200:203], v158 offset:18432
	ds_read_b128 v[204:207], v158 offset:19456
	ds_read_b128 v[210:213], v158 offset:20480
	ds_read_b128 v[214:217], v158 offset:21504
	ds_read_b128 v[218:221], v158 offset:22528
	ds_read_b128 v[222:225], v158 offset:23552
	global_load_lds_dwordx4 v[226:227], off
	v_lshl_add_u64 v[228:229], v[226:227], 0, s[22:23]
	s_add_i32 m0, s20, 0x2000
	s_add_i32 s20, s34, s10
	global_load_lds_dwordx4 v[228:229], off
	v_lshl_add_u64 v[228:229], v[226:227], 0, s[36:37]
	s_mov_b32 m0, s20
	s_nop 0
	global_load_lds_dwordx4 v[228:229], off
	v_lshl_add_u64 v[228:229], v[226:227], 0, s[38:39]
	s_add_i32 m0, s20, 0x2000
	s_nop 0
	global_load_lds_dwordx4 v[228:229], off
	v_lshl_add_u64 v[228:229], s[6:7], 0, v[134:135]
	s_mov_b32 m0, s11
	v_lshl_add_u64 v[230:231], v[228:229], 0, s[22:23]
	global_load_lds_dwordx4 v[228:229], off
	s_mov_b32 m0, s14
	s_nop 0
	global_load_lds_dwordx4 v[230:231], off
	s_waitcnt vmcnt(8)
	s_waitcnt lgkmcnt(0)
	s_barrier
; #define G8_MMA(ai, bj, At, Bt) do { __builtin_amdgcn_s_setprio(1); _Pragma("unroll") for (int m = 0; m < 4; ++m) _Pragma("unroll") for (int n = 0; n < 2; ++n) _Pragma("unroll") for (int k = 0; k < 2; ++k) \
;         acc[ai][bj][m][n] = __builtin_amdgcn_mfma_f32_16x16x32_bf16(Bt[n][k], At[m][k], acc[ai][bj][m][n], 0, 0, 0); __builtin_amdgcn_s_setprio(0); } while (0)
; #define G8_WAIT_V(n) asm volatile("s_waitcnt vmcnt(" #n ")" ::: "memory")
; #define G8_WAIT_L(n) asm volatile("s_waitcnt lgkmcnt(" #n ")" ::: "memory")
; #define G8_BAR __builtin_amdgcn_s_barrier()
; #define G8_SCHED __builtin_amdgcn_sched_barrier(0)
; template <class P>
; __device__ __forceinline__ void gemm_phase(LAS unsigned char* lds, const P& p, const int G, const int c) {
;     ...
;             G8_WAIT_V(8); G8_WAIT_L(0); G8_BAR; G8_MMA(1, 0, At, B0); G8_MMA(1, 1, At, B1); G8_BAR; G8_SCHED;
	s_waitcnt lgkmcnt(0)
	v_mfma_f32_16x16x32_bf16 v[62:65], v[160:163], v[192:195], v[62:65]
	v_mfma_f32_16x16x32_bf16 v[58:61], v[168:171], v[192:195], v[58:61]
	v_mfma_f32_16x16x32_bf16 v[54:57], v[160:163], v[200:203], v[54:57]
	v_mfma_f32_16x16x32_bf16 v[50:53], v[168:171], v[200:203], v[50:53]
	v_mfma_f32_16x16x32_bf16 v[38:41], v[160:163], v[210:213], v[38:41]
	v_mfma_f32_16x16x32_bf16 v[34:37], v[168:171], v[210:213], v[34:37]
	v_mfma_f32_16x16x32_bf16 v[22:25], v[160:163], v[218:221], v[22:25]
	v_mfma_f32_16x16x32_bf16 v[18:21], v[168:171], v[218:221], v[18:21]
	v_mfma_f32_16x16x32_bf16 v[62:65], v[164:167], v[196:199], v[62:65]
	v_mfma_f32_16x16x32_bf16 v[58:61], v[172:175], v[196:199], v[58:61]
	v_mfma_f32_16x16x32_bf16 v[54:57], v[164:167], v[204:207], v[54:57]
	v_mfma_f32_16x16x32_bf16 v[50:53], v[172:175], v[204:207], v[50:53]
	v_mfma_f32_16x16x32_bf16 v[38:41], v[164:167], v[214:217], v[38:41]
	v_mfma_f32_16x16x32_bf16 v[34:37], v[172:175], v[214:217], v[34:37]
	v_mfma_f32_16x16x32_bf16 v[22:25], v[164:167], v[222:225], v[22:25]
	v_mfma_f32_16x16x32_bf16 v[18:21], v[172:175], v[222:225], v[18:21]
	v_mfma_f32_16x16x32_bf16 v[46:49], v[176:179], v[192:195], v[46:49]
	v_mfma_f32_16x16x32_bf16 v[42:45], v[184:187], v[192:195], v[42:45]
	v_mfma_f32_16x16x32_bf16 v[30:33], v[176:179], v[200:203], v[30:33]
	v_mfma_f32_16x16x32_bf16 v[26:29], v[184:187], v[200:203], v[26:29]
	v_mfma_f32_16x16x32_bf16 v[14:17], v[176:179], v[210:213], v[14:17]
	v_mfma_f32_16x16x32_bf16 v[10:13], v[184:187], v[210:213], v[10:13]
	v_mfma_f32_16x16x32_bf16 v[6:9], v[176:179], v[218:221], v[6:9]
	v_mfma_f32_16x16x32_bf16 v[2:5], v[184:187], v[218:221], v[2:5]
	v_mfma_f32_16x16x32_bf16 v[46:49], v[180:183], v[196:199], v[46:49]
	v_mfma_f32_16x16x32_bf16 v[42:45], v[188:191], v[196:199], v[42:45]
	v_mfma_f32_16x16x32_bf16 v[30:33], v[180:183], v[204:207], v[30:33]
	v_mfma_f32_16x16x32_bf16 v[26:29], v[188:191], v[204:207], v[26:29]
	v_mfma_f32_16x16x32_bf16 v[14:17], v[180:183], v[214:217], v[14:17]
	v_mfma_f32_16x16x32_bf16 v[10:13], v[188:191], v[214:217], v[10:13]
	v_mfma_f32_16x16x32_bf16 v[6:9], v[180:183], v[222:225], v[6:9]
	v_mfma_f32_16x16x32_bf16 v[2:5], v[188:191], v[222:225], v[2:5]
; #define G8_STA(bufoff, ptr, sg, h) G8_STAGE1(bufoff, (ptr) + (h) * ((sg) ? hA1 : hA0), ((sg) ? voffA1 : voffA0), ((sg) ? r64A1 : r64A0))
; #define G8_STB(bufoff, ptr, sg, h) G8_STAGE1(bufoff, (ptr) + (h) * ((sg) ? hB1 : hB0), ((sg) ? voffB1 : voffB0), ((sg) ? r64B1 : r64B0))
; #define G8_LDA(dst, b, h) do { _Pragma("unroll") for (int m = 0; m < 4; ++m) _Pragma("unroll") for (int k = 0; k < 2; ++k) dst[m][k] = *(const LAS bf16x8*)(lds + G8_SA(b, h) + aoff + m * 2048 + k * 1024); } while (0)
; #define G8_LDB(dst, b, h) do { _Pragma("unroll") for (int n = 0; n < 2; ++n) _Pragma("unroll") for (int k = 0; k < 2; ++k) dst[n][k] = *(const LAS bf16x8*)(lds + G8_SB(b, h) + boff + n * 2048 + k * 1024); } while (0)
; #define G8_MMA(ai, bj, At, Bt) do { __builtin_amdgcn_s_setprio(1); _Pragma("unroll") for (int m = 0; m < 4; ++m) _Pragma("unroll") for (int n = 0; n < 2; ++n) _Pragma("unroll") for (int k = 0; k < 2; ++k) \
;         acc[ai][bj][m][n] = __builtin_amdgcn_mfma_f32_16x16x32_bf16(Bt[n][k], At[m][k], acc[ai][bj][m][n], 0, 0, 0); __builtin_amdgcn_s_setprio(0); } while (0)
; #define G8_WAIT_V(n) asm volatile("s_waitcnt vmcnt(" #n ")" ::: "memory")
; #define G8_WAIT_L(n) asm volatile("s_waitcnt lgkmcnt(" #n ")" ::: "memory")
; #define G8_BAR __builtin_amdgcn_s_barrier()
; #define G8_SCHED __builtin_amdgcn_sched_barrier(0)
; template <class P>
; __device__ __forceinline__ void gemm_phase(LAS unsigned char* lds, const P& p, const int G, const int c) {
;     ...
;             G8_LDB(B0, 1, 0); G8_LDB(B1, 1, 1); G8_SCHED; G8_LDA(At, 1, 0); G8_STA(G8_SA(0, 1), a2, sg2, 1);
;             G8_WAIT_V(8); G8_WAIT_L(0); G8_BAR; G8_MMA(0, 0, At, B0); G8_MMA(0, 1, At, B1); G8_BAR; G8_SCHED;
;             G8_LDA(At, 1, 1); G8_STB(G8_SB(1, 0), b3, sg2, 0); G8_STB(G8_SB(1, 1), b3, sg2, 1); G8_STA(G8_SA(1, 0), a3, sg2, 0);
;             G8_WAIT_V(8); G8_WAIT_L(0); G8_BAR; G8_MMA(1, 0, At, B0); G8_MMA(1, 1, At, B1); G8_BAR; G8_SCHED;
;         }
.Lmid_539:
	s_barrier
	s_add_i32 s35, 0, 0x18000
	v_add_u32_e32 v130, s35, v156
	s_add_i32 s20, 0, 0x1c000
	ds_read_b128 v[160:163], v130
	ds_read_b128 v[164:167], v130 offset:1024
	ds_read_b128 v[168:171], v130 offset:2048
	ds_read_b128 v[172:175], v130 offset:3072
	v_add_u32_e32 v130, s20, v156
	ds_read_b128 v[176:179], v130
	ds_read_b128 v[180:183], v130 offset:1024
	ds_read_b128 v[184:187], v130 offset:2048
	ds_read_b128 v[188:191], v130 offset:3072
	s_mov_b32 m0, s15
	v_lshl_add_u64 v[230:231], v[228:229], 0, s[36:37]
	ds_read_b128 v[192:195], v158 offset:32768
	ds_read_b128 v[196:199], v158 offset:33792
	ds_read_b128 v[200:203], v158 offset:34816
	ds_read_b128 v[204:207], v158 offset:35840
	ds_read_b128 v[210:213], v158 offset:36864
	ds_read_b128 v[214:217], v158 offset:37888
	ds_read_b128 v[218:221], v158 offset:38912
	ds_read_b128 v[222:225], v158 offset:39936
	global_load_lds_dwordx4 v[230:231], off
	v_lshl_add_u64 v[230:231], v[228:229], 0, s[38:39]
	s_mov_b32 m0, s16
	s_nop 0
	global_load_lds_dwordx4 v[230:231], off
	s_waitcnt vmcnt(8)
	s_waitcnt lgkmcnt(0)
	s_barrier
	s_waitcnt lgkmcnt(0)
	v_mfma_f32_16x16x32_bf16 v[126:129], v[160:163], v[192:195], v[126:129]
	v_mfma_f32_16x16x32_bf16 v[122:125], v[168:171], v[192:195], v[122:125]
	v_mfma_f32_16x16x32_bf16 v[118:121], v[160:163], v[200:203], v[118:121]
	v_mfma_f32_16x16x32_bf16 v[114:117], v[168:171], v[200:203], v[114:117]
	v_mfma_f32_16x16x32_bf16 v[102:105], v[160:163], v[210:213], v[102:105]
	v_mfma_f32_16x16x32_bf16 v[98:101], v[168:171], v[210:213], v[98:101]
	v_mfma_f32_16x16x32_bf16 v[86:89], v[160:163], v[218:221], v[86:89]
	v_mfma_f32_16x16x32_bf16 v[82:85], v[168:171], v[218:221], v[82:85]
	v_mfma_f32_16x16x32_bf16 v[126:129], v[164:167], v[196:199], v[126:129]
	v_mfma_f32_16x16x32_bf16 v[122:125], v[172:175], v[196:199], v[122:125]
	v_mfma_f32_16x16x32_bf16 v[118:121], v[164:167], v[204:207], v[118:121]
	v_mfma_f32_16x16x32_bf16 v[114:117], v[172:175], v[204:207], v[114:117]
	v_mfma_f32_16x16x32_bf16 v[102:105], v[164:167], v[214:217], v[102:105]
	v_mfma_f32_16x16x32_bf16 v[98:101], v[172:175], v[214:217], v[98:101]
	v_mfma_f32_16x16x32_bf16 v[86:89], v[164:167], v[222:225], v[86:89]
	v_mfma_f32_16x16x32_bf16 v[82:85], v[172:175], v[222:225], v[82:85]
	v_mfma_f32_16x16x32_bf16 v[110:113], v[176:179], v[192:195], v[110:113]
	v_mfma_f32_16x16x32_bf16 v[106:109], v[184:187], v[192:195], v[106:109]
	v_mfma_f32_16x16x32_bf16 v[94:97], v[176:179], v[200:203], v[94:97]
	v_mfma_f32_16x16x32_bf16 v[90:93], v[184:187], v[200:203], v[90:93]
	v_mfma_f32_16x16x32_bf16 v[78:81], v[176:179], v[210:213], v[78:81]
	v_mfma_f32_16x16x32_bf16 v[74:77], v[184:187], v[210:213], v[74:77]
	v_mfma_f32_16x16x32_bf16 v[70:73], v[176:179], v[218:221], v[70:73]
	v_mfma_f32_16x16x32_bf16 v[66:69], v[184:187], v[218:221], v[66:69]
	v_mfma_f32_16x16x32_bf16 v[110:113], v[180:183], v[196:199], v[110:113]
	v_mfma_f32_16x16x32_bf16 v[106:109], v[188:191], v[196:199], v[106:109]
	v_mfma_f32_16x16x32_bf16 v[94:97], v[180:183], v[204:207], v[94:97]
	v_mfma_f32_16x16x32_bf16 v[90:93], v[188:191], v[204:207], v[90:93]
	v_mfma_f32_16x16x32_bf16 v[78:81], v[180:183], v[214:217], v[78:81]
	v_mfma_f32_16x16x32_bf16 v[74:77], v[188:191], v[214:217], v[74:77]
	v_mfma_f32_16x16x32_bf16 v[70:73], v[180:183], v[222:225], v[70:73]
	v_mfma_f32_16x16x32_bf16 v[66:69], v[188:191], v[222:225], v[66:69]
	s_barrier
	s_add_i32 s6, s35, s10
	v_lshl_add_u64 v[230:231], v[226:227], 0, s[40:41]
	s_mov_b32 m0, s6
	ds_read_b128 v[192:195], v158 offset:49152
	ds_read_b128 v[196:199], v158 offset:50176
	ds_read_b128 v[200:203], v158 offset:51200
	ds_read_b128 v[204:207], v158 offset:52224
	ds_read_b128 v[210:213], v158 offset:53248
	ds_read_b128 v[214:217], v158 offset:54272
	ds_read_b128 v[218:221], v158 offset:55296
	ds_read_b128 v[222:225], v158 offset:56320
	global_load_lds_dwordx4 v[230:231], off
	v_lshl_add_u64 v[230:231], v[226:227], 0, s[42:43]
	s_add_i32 m0, s6, 0x2000
	s_add_i32 s6, s20, s10
	global_load_lds_dwordx4 v[230:231], off
	v_lshl_add_u64 v[230:231], v[226:227], 0, s[48:49]
	s_mov_b32 m0, s6
	v_lshl_add_u64 v[226:227], v[226:227], 0, s[52:53]
	global_load_lds_dwordx4 v[230:231], off
	s_add_i32 m0, s6, 0x2000
	s_nop 0
	global_load_lds_dwordx4 v[226:227], off
	v_lshl_add_u64 v[226:227], v[228:229], 0, s[8:9]
	s_mov_b32 m0, s24
	s_nop 0
	global_load_lds_dwordx4 v[226:227], off
	v_lshl_add_u64 v[226:227], v[228:229], 0, s[44:45]
	s_mov_b32 m0, s25
	s_nop 0
	global_load_lds_dwordx4 v[226:227], off
	s_waitcnt vmcnt(8)
	s_waitcnt lgkmcnt(0)
	s_barrier
	s_waitcnt lgkmcnt(0)
	v_mfma_f32_16x16x32_bf16 v[62:65], v[160:163], v[192:195], v[62:65]
	v_mfma_f32_16x16x32_bf16 v[58:61], v[168:171], v[192:195], v[58:61]
	v_mfma_f32_16x16x32_bf16 v[54:57], v[160:163], v[200:203], v[54:57]
	v_mfma_f32_16x16x32_bf16 v[50:53], v[168:171], v[200:203], v[50:53]
	v_mfma_f32_16x16x32_bf16 v[38:41], v[160:163], v[210:213], v[38:41]
	v_mfma_f32_16x16x32_bf16 v[34:37], v[168:171], v[210:213], v[34:37]
	v_mfma_f32_16x16x32_bf16 v[22:25], v[160:163], v[218:221], v[22:25]
	v_mfma_f32_16x16x32_bf16 v[18:21], v[168:171], v[218:221], v[18:21]
	v_mfma_f32_16x16x32_bf16 v[62:65], v[164:167], v[196:199], v[62:65]
	v_mfma_f32_16x16x32_bf16 v[58:61], v[172:175], v[196:199], v[58:61]
	v_mfma_f32_16x16x32_bf16 v[54:57], v[164:167], v[204:207], v[54:57]
	v_mfma_f32_16x16x32_bf16 v[50:53], v[172:175], v[204:207], v[50:53]
	v_mfma_f32_16x16x32_bf16 v[38:41], v[164:167], v[214:217], v[38:41]
	v_mfma_f32_16x16x32_bf16 v[34:37], v[172:175], v[214:217], v[34:37]
	v_mfma_f32_16x16x32_bf16 v[22:25], v[164:167], v[222:225], v[22:25]
	v_mfma_f32_16x16x32_bf16 v[18:21], v[172:175], v[222:225], v[18:21]
	v_mfma_f32_16x16x32_bf16 v[46:49], v[176:179], v[192:195], v[46:49]
	v_mfma_f32_16x16x32_bf16 v[42:45], v[184:187], v[192:195], v[42:45]
	v_mfma_f32_16x16x32_bf16 v[30:33], v[176:179], v[200:203], v[30:33]
	v_mfma_f32_16x16x32_bf16 v[26:29], v[184:187], v[200:203], v[26:29]
	v_mfma_f32_16x16x32_bf16 v[14:17], v[176:179], v[210:213], v[14:17]
	v_mfma_f32_16x16x32_bf16 v[10:13], v[184:187], v[210:213], v[10:13]
	v_mfma_f32_16x16x32_bf16 v[6:9], v[176:179], v[218:221], v[6:9]
	v_mfma_f32_16x16x32_bf16 v[2:5], v[184:187], v[218:221], v[2:5]
	v_mfma_f32_16x16x32_bf16 v[46:49], v[180:183], v[196:199], v[46:49]
	v_mfma_f32_16x16x32_bf16 v[42:45], v[188:191], v[196:199], v[42:45]
	v_mfma_f32_16x16x32_bf16 v[30:33], v[180:183], v[204:207], v[30:33]
	v_mfma_f32_16x16x32_bf16 v[26:29], v[188:191], v[204:207], v[26:29]
	v_mfma_f32_16x16x32_bf16 v[14:17], v[180:183], v[214:217], v[14:17]
	v_mfma_f32_16x16x32_bf16 v[10:13], v[188:191], v[214:217], v[10:13]
	v_mfma_f32_16x16x32_bf16 v[6:9], v[180:183], v[222:225], v[6:9]
	v_mfma_f32_16x16x32_bf16 v[2:5], v[188:191], v[222:225], v[2:5]
	s_add_i32 s47, s47, 2
	s_add_u32 s28, s28, 0x40000
	s_addc_u32 s29, s29, 0
	s_add_u32 s94, s94, 0x10000
	s_addc_u32 s95, s95, 0
	s_cmp_gt_u32 s47, 5
	s_cbranch_scc0 .LBB0_539
	s_barrier
	s_and_b64 vcc, exec, s[86:87]
	s_cbranch_vccz .LBB0_542
	s_barrier

; #define G8_STA(bufoff, ptr, sg, h) G8_STAGE1(bufoff, (ptr) + (h) * ((sg) ? hA1 : hA0), ((sg) ? voffA1 : voffA0), ((sg) ? r64A1 : r64A0))
; #define G8_STB(bufoff, ptr, sg, h) G8_STAGE1(bufoff, (ptr) + (h) * ((sg) ? hB1 : hB0), ((sg) ? voffB1 : voffB0), ((sg) ? r64B1 : r64B0))
; #define G8_LDA(dst, b, h) do { _Pragma("unroll") for (int m = 0; m < 4; ++m) _Pragma("unroll") for (int k = 0; k < 2; ++k) dst[m][k] = *(const LAS bf16x8*)(lds + G8_SA(b, h) + aoff + m * 2048 + k * 1024); } while (0)
; #define G8_LDB(dst, b, h) do { _Pragma("unroll") for (int n = 0; n < 2; ++n) _Pragma("unroll") for (int k = 0; k < 2; ++k) dst[n][k] = *(const LAS bf16x8*)(lds + G8_SB(b, h) + boff + n * 2048 + k * 1024); } while (0)
; #define G8_MMA(ai, bj, At, Bt) do { __builtin_amdgcn_s_setprio(1); _Pragma("unroll") for (int m = 0; m < 4; ++m) _Pragma("unroll") for (int n = 0; n < 2; ++n) _Pragma("unroll") for (int k = 0; k < 2; ++k) \
;         acc[ai][bj][m][n] = __builtin_amdgcn_mfma_f32_16x16x32_bf16(Bt[n][k], At[m][k], acc[ai][bj][m][n], 0, 0, 0); __builtin_amdgcn_s_setprio(0); } while (0)
; #define G8_BAR __builtin_amdgcn_s_barrier()
; template <class P>
; __device__ __forceinline__ void gemm_phase(LAS unsigned char* lds, const P& p, const int G, const int c) {
;     ...
;         for (int t = 0; t < nt; t += 2) {
;             const bool last = (t == nt - 2);
;             const bool sg1 = (NS > 1) && (t + 1 >= nt0);
;             const bool sg2 = (NS > 1) && !last && (t + 2 >= nt0);
;             const char* a1 = sg1 ? cA1 + (long)(t + 1 - nt0) * ksA1 : cA0 + (long)(t + 1) * ksA0;
;             const char* a2 = last ? nA0 : (sg2 ? cA1 + (long)(t + 2 - nt0) * ksA1 : cA0 + (long)(t + 2) * ksA0);
;             const char* b2 = last ? nB0 : (sg2 ? cB1 + (long)(t + 2 - nt0) * ksB1 : cB0 + (long)(t + 2) * ksB0);
;             const char* a3 = a2 + (sg2 ? ksA1 : ksA0); const char* b3 = b2 + (sg2 ? ksB1 : ksB0);
;             G8_LDB(B0, 0, 0); G8_LDB(B1, 0, 1); G8_SCHED; G8_LDA(At, 0, 0); G8_STA(G8_SA(1, 1), a1, sg1, 1);
;             G8_WAIT_V(8); G8_WAIT_L(0); G8_BAR; G8_MMA(0, 0, At, B0); G8_MMA(0, 1, At, B1); G8_BAR; G8_SCHED;
;             G8_LDA(At, 0, 1); G8_STB(G8_SB(0, 0), b2, sg2, 0); G8_STB(G8_SB(0, 1), b2, sg2, 1); G8_STA(G8_SA(0, 0), a2, sg2, 0);
;             G8_WAIT_V(8); G8_WAIT_L(0); G8_BAR; G8_MMA(1, 0, At, B0); G8_MMA(1, 1, At, B1); G8_BAR; G8_SCHED;
.LBB0_679:
	s_barrier
	v_add_u32_e32 v153, s50, v1
	ds_read_b128 v[170:173], v153
	ds_read_b128 v[174:177], v153 offset:1024
	ds_read_b128 v[178:181], v153 offset:2048
	ds_read_b128 v[182:185], v153 offset:3072
	v_add_u32_e32 v153, s51, v1
	ds_read_b128 v[186:189], v153
	ds_read_b128 v[190:193], v153 offset:1024
	ds_read_b128 v[194:197], v153 offset:2048
	ds_read_b128 v[198:201], v153 offset:3072
	s_and_b64 s[30:31], exec, s[30:31]
	s_cselect_b32 s31, s18, s59
	s_cselect_b32 s30, s19, s53
	v_lshl_add_u64 v[206:207], v[168:169], 0, s[62:63]
	v_lshl_add_u64 v[238:239], v[206:207], 0, s[40:41]
	s_add_i32 m0, s27, 0xc000
	ds_read_b128 v[202:205], v151
	ds_read_b128 v[210:213], v151 offset:1024
	ds_read_b128 v[214:217], v151 offset:2048
	ds_read_b128 v[218:221], v151 offset:3072
	ds_read_b128 v[222:225], v151 offset:4096
	ds_read_b128 v[226:229], v151 offset:5120
	ds_read_b128 v[230:233], v151 offset:6144
	ds_read_b128 v[234:237], v151 offset:7168
	global_load_lds_dwordx4 v[238:239], off
	v_lshl_add_u64 v[206:207], v[206:207], 0, s[42:43]
	s_add_i32 m0, s27, 0xe000
	s_nop 0
	global_load_lds_dwordx4 v[206:207], off
	s_waitcnt vmcnt(8)
	s_waitcnt lgkmcnt(0)
	s_barrier
	s_waitcnt lgkmcnt(0)
	v_mfma_f32_16x16x32_bf16 v[126:129], v[170:173], v[202:205], v[126:129]
	v_mfma_f32_16x16x32_bf16 v[122:125], v[178:181], v[202:205], v[122:125]
	v_mfma_f32_16x16x32_bf16 v[110:113], v[170:173], v[214:217], v[110:113]
	v_mfma_f32_16x16x32_bf16 v[106:109], v[178:181], v[214:217], v[106:109]
	v_mfma_f32_16x16x32_bf16 v[94:97], v[170:173], v[222:225], v[94:97]
	v_mfma_f32_16x16x32_bf16 v[90:93], v[178:181], v[222:225], v[90:93]
	v_mfma_f32_16x16x32_bf16 v[78:81], v[170:173], v[230:233], v[78:81]
	v_mfma_f32_16x16x32_bf16 v[74:77], v[178:181], v[230:233], v[74:77]
	v_mfma_f32_16x16x32_bf16 v[126:129], v[174:177], v[210:213], v[126:129]
	v_mfma_f32_16x16x32_bf16 v[122:125], v[182:185], v[210:213], v[122:125]
	v_mfma_f32_16x16x32_bf16 v[110:113], v[174:177], v[218:221], v[110:113]
	v_mfma_f32_16x16x32_bf16 v[106:109], v[182:185], v[218:221], v[106:109]
	v_mfma_f32_16x16x32_bf16 v[94:97], v[174:177], v[226:229], v[94:97]
	v_mfma_f32_16x16x32_bf16 v[90:93], v[182:185], v[226:229], v[90:93]
	v_mfma_f32_16x16x32_bf16 v[78:81], v[174:177], v[234:237], v[78:81]
	v_mfma_f32_16x16x32_bf16 v[74:77], v[182:185], v[234:237], v[74:77]
	v_mfma_f32_16x16x32_bf16 v[118:121], v[186:189], v[202:205], v[118:121]
	v_mfma_f32_16x16x32_bf16 v[114:117], v[194:197], v[202:205], v[114:117]
	v_mfma_f32_16x16x32_bf16 v[102:105], v[186:189], v[214:217], v[102:105]
	v_mfma_f32_16x16x32_bf16 v[98:101], v[194:197], v[214:217], v[98:101]
	v_mfma_f32_16x16x32_bf16 v[86:89], v[186:189], v[222:225], v[86:89]
	v_mfma_f32_16x16x32_bf16 v[82:85], v[194:197], v[222:225], v[82:85]
	v_mfma_f32_16x16x32_bf16 v[70:73], v[186:189], v[230:233], v[70:73]
	v_mfma_f32_16x16x32_bf16 v[66:69], v[194:197], v[230:233], v[66:69]
	v_mfma_f32_16x16x32_bf16 v[118:121], v[190:193], v[210:213], v[118:121]
	v_mfma_f32_16x16x32_bf16 v[114:117], v[198:201], v[210:213], v[114:117]
	v_mfma_f32_16x16x32_bf16 v[102:105], v[190:193], v[218:221], v[102:105]
	v_mfma_f32_16x16x32_bf16 v[98:101], v[198:201], v[218:221], v[98:101]
	v_mfma_f32_16x16x32_bf16 v[86:89], v[190:193], v[226:229], v[86:89]
	v_mfma_f32_16x16x32_bf16 v[82:85], v[198:201], v[226:229], v[82:85]
	v_mfma_f32_16x16x32_bf16 v[70:73], v[190:193], v[234:237], v[70:73]
	v_mfma_f32_16x16x32_bf16 v[66:69], v[198:201], v[234:237], v[66:69]
	s_barrier
	v_lshl_add_u64 v[206:207], s[30:31], 0, v[130:131]
	s_add_i32 s30, s50, s26
	s_mov_b32 m0, s30
	ds_read_b128 v[202:205], v151 offset:16384
	ds_read_b128 v[210:213], v151 offset:17408
	ds_read_b128 v[214:217], v151 offset:18432
	ds_read_b128 v[218:221], v151 offset:19456
	ds_read_b128 v[222:225], v151 offset:20480
	ds_read_b128 v[226:229], v151 offset:21504
	ds_read_b128 v[230:233], v151 offset:22528
	ds_read_b128 v[234:237], v151 offset:23552
	global_load_lds_dwordx4 v[206:207], off
	v_lshl_add_u64 v[238:239], v[206:207], 0, s[0:1]
	s_add_i32 m0, s30, 0x2000
	s_add_i32 s30, s51, s26
	global_load_lds_dwordx4 v[238:239], off
	v_lshl_add_u64 v[238:239], v[206:207], 0, s[4:5]
	s_mov_b32 m0, s30
	s_nop 0
	global_load_lds_dwordx4 v[238:239], off
	v_lshl_add_u64 v[238:239], v[206:207], 0, s[6:7]
	s_add_i32 m0, s30, 0x2000
	s_nop 0
	global_load_lds_dwordx4 v[238:239], off
	v_lshl_add_u64 v[238:239], s[28:29], 0, v[132:133]
	s_mov_b32 m0, s27
	v_lshl_add_u64 v[240:241], v[238:239], 0, s[0:1]
	global_load_lds_dwordx4 v[238:239], off
	s_mov_b32 m0, s33
	s_nop 0
	global_load_lds_dwordx4 v[240:241], off
	s_waitcnt vmcnt(8)
	s_waitcnt lgkmcnt(0)
	s_barrier
	s_waitcnt lgkmcnt(0)
	v_mfma_f32_16x16x32_bf16 v[62:65], v[170:173], v[202:205], v[62:65]
	v_mfma_f32_16x16x32_bf16 v[58:61], v[178:181], v[202:205], v[58:61]
	v_mfma_f32_16x16x32_bf16 v[46:49], v[170:173], v[214:217], v[46:49]
	v_mfma_f32_16x16x32_bf16 v[42:45], v[178:181], v[214:217], v[42:45]
	v_mfma_f32_16x16x32_bf16 v[30:33], v[170:173], v[222:225], v[30:33]
	v_mfma_f32_16x16x32_bf16 v[26:29], v[178:181], v[222:225], v[26:29]
	v_mfma_f32_16x16x32_bf16 v[14:17], v[170:173], v[230:233], v[14:17]
	v_mfma_f32_16x16x32_bf16 v[10:13], v[178:181], v[230:233], v[10:13]
	v_mfma_f32_16x16x32_bf16 v[62:65], v[174:177], v[210:213], v[62:65]
	v_mfma_f32_16x16x32_bf16 v[58:61], v[182:185], v[210:213], v[58:61]
	v_mfma_f32_16x16x32_bf16 v[46:49], v[174:177], v[218:221], v[46:49]
	v_mfma_f32_16x16x32_bf16 v[42:45], v[182:185], v[218:221], v[42:45]
	v_mfma_f32_16x16x32_bf16 v[30:33], v[174:177], v[226:229], v[30:33]
	v_mfma_f32_16x16x32_bf16 v[26:29], v[182:185], v[226:229], v[26:29]
	v_mfma_f32_16x16x32_bf16 v[14:17], v[174:177], v[234:237], v[14:17]
	v_mfma_f32_16x16x32_bf16 v[10:13], v[182:185], v[234:237], v[10:13]
	v_mfma_f32_16x16x32_bf16 v[54:57], v[186:189], v[202:205], v[54:57]
	v_mfma_f32_16x16x32_bf16 v[50:53], v[194:197], v[202:205], v[50:53]
	v_mfma_f32_16x16x32_bf16 v[38:41], v[186:189], v[214:217], v[38:41]
	v_mfma_f32_16x16x32_bf16 v[34:37], v[194:197], v[214:217], v[34:37]
	v_mfma_f32_16x16x32_bf16 v[22:25], v[186:189], v[222:225], v[22:25]
	v_mfma_f32_16x16x32_bf16 v[18:21], v[194:197], v[222:225], v[18:21]
	v_mfma_f32_16x16x32_bf16 v[6:9], v[186:189], v[230:233], v[6:9]
	v_mfma_f32_16x16x32_bf16 v[2:5], v[194:197], v[230:233], v[2:5]
	v_mfma_f32_16x16x32_bf16 v[54:57], v[190:193], v[210:213], v[54:57]
	v_mfma_f32_16x16x32_bf16 v[50:53], v[198:201], v[210:213], v[50:53]
	v_mfma_f32_16x16x32_bf16 v[38:41], v[190:193], v[218:221], v[38:41]
	v_mfma_f32_16x16x32_bf16 v[34:37], v[198:201], v[218:221], v[34:37]
	v_mfma_f32_16x16x32_bf16 v[22:25], v[190:193], v[226:229], v[22:25]
	v_mfma_f32_16x16x32_bf16 v[18:21], v[198:201], v[226:229], v[18:21]
	v_mfma_f32_16x16x32_bf16 v[6:9], v[190:193], v[234:237], v[6:9]
	v_mfma_f32_16x16x32_bf16 v[2:5], v[198:201], v[234:237], v[2:5]
; #define G8_STA(bufoff, ptr, sg, h) G8_STAGE1(bufoff, (ptr) + (h) * ((sg) ? hA1 : hA0), ((sg) ? voffA1 : voffA0), ((sg) ? r64A1 : r64A0))
; #define G8_STB(bufoff, ptr, sg, h) G8_STAGE1(bufoff, (ptr) + (h) * ((sg) ? hB1 : hB0), ((sg) ? voffB1 : voffB0), ((sg) ? r64B1 : r64B0))
; #define G8_LDA(dst, b, h) do { _Pragma("unroll") for (int m = 0; m < 4; ++m) _Pragma("unroll") for (int k = 0; k < 2; ++k) dst[m][k] = *(const LAS bf16x8*)(lds + G8_SA(b, h) + aoff + m * 2048 + k * 1024); } while (0)
; #define G8_LDB(dst, b, h) do { _Pragma("unroll") for (int n = 0; n < 2; ++n) _Pragma("unroll") for (int k = 0; k < 2; ++k) dst[n][k] = *(const LAS bf16x8*)(lds + G8_SB(b, h) + boff + n * 2048 + k * 1024); } while (0)
; #define G8_MMA(ai, bj, At, Bt) do { __builtin_amdgcn_s_setprio(1); _Pragma("unroll") for (int m = 0; m < 4; ++m) _Pragma("unroll") for (int n = 0; n < 2; ++n) _Pragma("unroll") for (int k = 0; k < 2; ++k) \
;         acc[ai][bj][m][n] = __builtin_amdgcn_mfma_f32_16x16x32_bf16(Bt[n][k], At[m][k], acc[ai][bj][m][n], 0, 0, 0); __builtin_amdgcn_s_setprio(0); } while (0)
; #define G8_WAIT_V(n) asm volatile("s_waitcnt vmcnt(" #n ")" ::: "memory")
; #define G8_WAIT_L(n) asm volatile("s_waitcnt lgkmcnt(" #n ")" ::: "memory")
; #define G8_BAR __builtin_amdgcn_s_barrier()
; #define G8_SCHED __builtin_amdgcn_sched_barrier(0)
; template <class P>
; __device__ __forceinline__ void gemm_phase(LAS unsigned char* lds, const P& p, const int G, const int c) {
;     ...
;             G8_LDB(B0, 1, 0); G8_LDB(B1, 1, 1); G8_SCHED; G8_LDA(At, 1, 0); G8_STA(G8_SA(0, 1), a2, sg2, 1);
;             G8_WAIT_V(8); G8_WAIT_L(0); G8_BAR; G8_MMA(0, 0, At, B0); G8_MMA(0, 1, At, B1); G8_BAR; G8_SCHED;
;             G8_LDA(At, 1, 1); G8_STB(G8_SB(1, 0), b3, sg2, 0); G8_STB(G8_SB(1, 1), b3, sg2, 1); G8_STA(G8_SA(1, 0), a3, sg2, 0);
;             G8_WAIT_V(8); G8_WAIT_L(0); G8_BAR; G8_MMA(1, 0, At, B0); G8_MMA(1, 1, At, B1); G8_BAR; G8_SCHED;
;         }
.Lmid_679:
	s_barrier
	s_add_i32 s28, 0, 0x18000
	v_add_u32_e32 v153, s28, v1
	s_add_i32 s29, 0, 0x1c000
	ds_read_b128 v[170:173], v153
	ds_read_b128 v[174:177], v153 offset:1024
	ds_read_b128 v[178:181], v153 offset:2048
	ds_read_b128 v[182:185], v153 offset:3072
	v_add_u32_e32 v153, s29, v1
	ds_read_b128 v[186:189], v153
	ds_read_b128 v[190:193], v153 offset:1024
	ds_read_b128 v[194:197], v153 offset:2048
	ds_read_b128 v[198:201], v153 offset:3072
	s_mov_b32 m0, s34
	v_lshl_add_u64 v[240:241], v[238:239], 0, s[4:5]
	ds_read_b128 v[202:205], v151 offset:32768
	ds_read_b128 v[210:213], v151 offset:33792
	ds_read_b128 v[214:217], v151 offset:34816
	ds_read_b128 v[218:221], v151 offset:35840
	ds_read_b128 v[222:225], v151 offset:36864
	ds_read_b128 v[226:229], v151 offset:37888
	ds_read_b128 v[230:233], v151 offset:38912
	ds_read_b128 v[234:237], v151 offset:39936
	global_load_lds_dwordx4 v[240:241], off
	v_lshl_add_u64 v[240:241], v[238:239], 0, s[6:7]
	s_mov_b32 m0, s35
	s_nop 0
	global_load_lds_dwordx4 v[240:241], off
	s_waitcnt vmcnt(8)
	s_waitcnt lgkmcnt(0)
	s_barrier
	s_waitcnt lgkmcnt(0)
	v_mfma_f32_16x16x32_bf16 v[126:129], v[170:173], v[202:205], v[126:129]
	v_mfma_f32_16x16x32_bf16 v[122:125], v[178:181], v[202:205], v[122:125]
	v_mfma_f32_16x16x32_bf16 v[110:113], v[170:173], v[214:217], v[110:113]
	v_mfma_f32_16x16x32_bf16 v[106:109], v[178:181], v[214:217], v[106:109]
	v_mfma_f32_16x16x32_bf16 v[94:97], v[170:173], v[222:225], v[94:97]
	v_mfma_f32_16x16x32_bf16 v[90:93], v[178:181], v[222:225], v[90:93]
	v_mfma_f32_16x16x32_bf16 v[78:81], v[170:173], v[230:233], v[78:81]
	v_mfma_f32_16x16x32_bf16 v[74:77], v[178:181], v[230:233], v[74:77]
	v_mfma_f32_16x16x32_bf16 v[126:129], v[174:177], v[210:213], v[126:129]
	v_mfma_f32_16x16x32_bf16 v[122:125], v[182:185], v[210:213], v[122:125]
	v_mfma_f32_16x16x32_bf16 v[110:113], v[174:177], v[218:221], v[110:113]
	v_mfma_f32_16x16x32_bf16 v[106:109], v[182:185], v[218:221], v[106:109]
	v_mfma_f32_16x16x32_bf16 v[94:97], v[174:177], v[226:229], v[94:97]
	v_mfma_f32_16x16x32_bf16 v[90:93], v[182:185], v[226:229], v[90:93]
	v_mfma_f32_16x16x32_bf16 v[78:81], v[174:177], v[234:237], v[78:81]
	v_mfma_f32_16x16x32_bf16 v[74:77], v[182:185], v[234:237], v[74:77]
	v_mfma_f32_16x16x32_bf16 v[118:121], v[186:189], v[202:205], v[118:121]
	v_mfma_f32_16x16x32_bf16 v[114:117], v[194:197], v[202:205], v[114:117]
	v_mfma_f32_16x16x32_bf16 v[102:105], v[186:189], v[214:217], v[102:105]
	v_mfma_f32_16x16x32_bf16 v[98:101], v[194:197], v[214:217], v[98:101]
	v_mfma_f32_16x16x32_bf16 v[86:89], v[186:189], v[222:225], v[86:89]
	v_mfma_f32_16x16x32_bf16 v[82:85], v[194:197], v[222:225], v[82:85]
	v_mfma_f32_16x16x32_bf16 v[70:73], v[186:189], v[230:233], v[70:73]
	v_mfma_f32_16x16x32_bf16 v[66:69], v[194:197], v[230:233], v[66:69]
	v_mfma_f32_16x16x32_bf16 v[118:121], v[190:193], v[210:213], v[118:121]
	v_mfma_f32_16x16x32_bf16 v[114:117], v[198:201], v[210:213], v[114:117]
	v_mfma_f32_16x16x32_bf16 v[102:105], v[190:193], v[218:221], v[102:105]
	v_mfma_f32_16x16x32_bf16 v[98:101], v[198:201], v[218:221], v[98:101]
	v_mfma_f32_16x16x32_bf16 v[86:89], v[190:193], v[226:229], v[86:89]
	v_mfma_f32_16x16x32_bf16 v[82:85], v[198:201], v[226:229], v[82:85]
	v_mfma_f32_16x16x32_bf16 v[70:73], v[190:193], v[234:237], v[70:73]
	v_mfma_f32_16x16x32_bf16 v[66:69], v[198:201], v[234:237], v[66:69]
	s_barrier
	s_add_i32 s28, s28, s26
	v_lshl_add_u64 v[240:241], v[206:207], 0, s[12:13]
	s_mov_b32 m0, s28
	ds_read_b128 v[202:205], v151 offset:49152
	ds_read_b128 v[210:213], v151 offset:50176
	ds_read_b128 v[214:217], v151 offset:51200
	ds_read_b128 v[218:221], v151 offset:52224
	ds_read_b128 v[222:225], v151 offset:53248
	ds_read_b128 v[226:229], v151 offset:54272
	ds_read_b128 v[230:233], v151 offset:55296
	ds_read_b128 v[234:237], v151 offset:56320
	global_load_lds_dwordx4 v[240:241], off
	v_lshl_add_u64 v[240:241], v[206:207], 0, s[14:15]
	s_add_i32 m0, s28, 0x2000
	s_add_i32 s28, s29, s26
	global_load_lds_dwordx4 v[240:241], off
	v_lshl_add_u64 v[240:241], v[206:207], 0, s[22:23]
	s_mov_b32 m0, s28
	v_lshl_add_u64 v[206:207], v[206:207], 0, s[36:37]
	global_load_lds_dwordx4 v[240:241], off
	s_add_i32 m0, s28, 0x2000
	s_nop 0
	global_load_lds_dwordx4 v[206:207], off
	v_lshl_add_u64 v[206:207], v[238:239], 0, s[16:17]
	s_mov_b32 m0, s46
	s_nop 0
	global_load_lds_dwordx4 v[206:207], off
	v_lshl_add_u64 v[206:207], v[238:239], 0, s[20:21]
	s_mov_b32 m0, s47
	s_nop 0
	global_load_lds_dwordx4 v[206:207], off
	s_waitcnt vmcnt(8)
	s_waitcnt lgkmcnt(0)
	s_barrier
	s_waitcnt lgkmcnt(0)
	v_mfma_f32_16x16x32_bf16 v[62:65], v[170:173], v[202:205], v[62:65]
	v_mfma_f32_16x16x32_bf16 v[58:61], v[178:181], v[202:205], v[58:61]
	v_mfma_f32_16x16x32_bf16 v[46:49], v[170:173], v[214:217], v[46:49]
	v_mfma_f32_16x16x32_bf16 v[42:45], v[178:181], v[214:217], v[42:45]
	v_mfma_f32_16x16x32_bf16 v[30:33], v[170:173], v[222:225], v[30:33]
	v_mfma_f32_16x16x32_bf16 v[26:29], v[178:181], v[222:225], v[26:29]
	v_mfma_f32_16x16x32_bf16 v[14:17], v[170:173], v[230:233], v[14:17]
	v_mfma_f32_16x16x32_bf16 v[10:13], v[178:181], v[230:233], v[10:13]
	v_mfma_f32_16x16x32_bf16 v[62:65], v[174:177], v[210:213], v[62:65]
	v_mfma_f32_16x16x32_bf16 v[58:61], v[182:185], v[210:213], v[58:61]
	v_mfma_f32_16x16x32_bf16 v[46:49], v[174:177], v[218:221], v[46:49]
	v_mfma_f32_16x16x32_bf16 v[42:45], v[182:185], v[218:221], v[42:45]
	v_mfma_f32_16x16x32_bf16 v[30:33], v[174:177], v[226:229], v[30:33]
	v_mfma_f32_16x16x32_bf16 v[26:29], v[182:185], v[226:229], v[26:29]
	v_mfma_f32_16x16x32_bf16 v[14:17], v[174:177], v[234:237], v[14:17]
	v_mfma_f32_16x16x32_bf16 v[10:13], v[182:185], v[234:237], v[10:13]
	v_mfma_f32_16x16x32_bf16 v[54:57], v[186:189], v[202:205], v[54:57]
	v_mfma_f32_16x16x32_bf16 v[50:53], v[194:197], v[202:205], v[50:53]
	v_mfma_f32_16x16x32_bf16 v[38:41], v[186:189], v[214:217], v[38:41]
	v_mfma_f32_16x16x32_bf16 v[34:37], v[194:197], v[214:217], v[34:37]
	v_mfma_f32_16x16x32_bf16 v[22:25], v[186:189], v[222:225], v[22:25]
	v_mfma_f32_16x16x32_bf16 v[18:21], v[194:197], v[222:225], v[18:21]
	v_mfma_f32_16x16x32_bf16 v[6:9], v[186:189], v[230:233], v[6:9]
	v_mfma_f32_16x16x32_bf16 v[2:5], v[194:197], v[230:233], v[2:5]
	v_mfma_f32_16x16x32_bf16 v[54:57], v[190:193], v[210:213], v[54:57]
	v_mfma_f32_16x16x32_bf16 v[50:53], v[198:201], v[210:213], v[50:53]
	v_mfma_f32_16x16x32_bf16 v[38:41], v[190:193], v[218:221], v[38:41]
	v_mfma_f32_16x16x32_bf16 v[34:37], v[198:201], v[218:221], v[34:37]
	v_mfma_f32_16x16x32_bf16 v[22:25], v[190:193], v[226:229], v[22:25]
	v_mfma_f32_16x16x32_bf16 v[18:21], v[198:201], v[226:229], v[18:21]
	v_mfma_f32_16x16x32_bf16 v[6:9], v[190:193], v[234:237], v[6:9]
	v_mfma_f32_16x16x32_bf16 v[2:5], v[198:201], v[234:237], v[2:5]
	s_add_i32 s66, s66, 2
	s_add_u32 s53, s53, 0x100000
	s_addc_u32 s59, s59, 0
	s_add_u32 s62, s62, 0x820000
	s_addc_u32 s63, s63, 0
	s_cmp_gt_u32 s66, 13
	s_cbranch_scc1 .Lrotx_679

; #define G8_STA(bufoff, ptr, sg, h) G8_STAGE1(bufoff, (ptr) + (h) * ((sg) ? hA1 : hA0), ((sg) ? voffA1 : voffA0), ((sg) ? r64A1 : r64A0))
; #define G8_STB(bufoff, ptr, sg, h) G8_STAGE1(bufoff, (ptr) + (h) * ((sg) ? hB1 : hB0), ((sg) ? voffB1 : voffB0), ((sg) ? r64B1 : r64B0))
; #define G8_LDA(dst, b, h) do { _Pragma("unroll") for (int m = 0; m < 4; ++m) _Pragma("unroll") for (int k = 0; k < 2; ++k) dst[m][k] = *(const LAS bf16x8*)(lds + G8_SA(b, h) + aoff + m * 2048 + k * 1024); } while (0)
; #define G8_LDB(dst, b, h) do { _Pragma("unroll") for (int n = 0; n < 2; ++n) _Pragma("unroll") for (int k = 0; k < 2; ++k) dst[n][k] = *(const LAS bf16x8*)(lds + G8_SB(b, h) + boff + n * 2048 + k * 1024); } while (0)
; #define G8_MMA(ai, bj, At, Bt) do { __builtin_amdgcn_s_setprio(1); _Pragma("unroll") for (int m = 0; m < 4; ++m) _Pragma("unroll") for (int n = 0; n < 2; ++n) _Pragma("unroll") for (int k = 0; k < 2; ++k) \
;         acc[ai][bj][m][n] = __builtin_amdgcn_mfma_f32_16x16x32_bf16(Bt[n][k], At[m][k], acc[ai][bj][m][n], 0, 0, 0); __builtin_amdgcn_s_setprio(0); } while (0)
; #define G8_BAR __builtin_amdgcn_s_barrier()
; template <class P>
; __device__ __forceinline__ void gemm_phase(LAS unsigned char* lds, const P& p, const int G, const int c) {
;     ...
;         for (int t = 0; t < nt; t += 2) {
;             const bool last = (t == nt - 2);
;             const bool sg1 = (NS > 1) && (t + 1 >= nt0);
;             const bool sg2 = (NS > 1) && !last && (t + 2 >= nt0);
;             const char* a1 = sg1 ? cA1 + (long)(t + 1 - nt0) * ksA1 : cA0 + (long)(t + 1) * ksA0;
;             const char* a2 = last ? nA0 : (sg2 ? cA1 + (long)(t + 2 - nt0) * ksA1 : cA0 + (long)(t + 2) * ksA0);
;             const char* b2 = last ? nB0 : (sg2 ? cB1 + (long)(t + 2 - nt0) * ksB1 : cB0 + (long)(t + 2) * ksB0);
;             const char* a3 = a2 + (sg2 ? ksA1 : ksA0); const char* b3 = b2 + (sg2 ? ksB1 : ksB0);
;             G8_LDB(B0, 0, 0); G8_LDB(B1, 0, 1); G8_SCHED; G8_LDA(At, 0, 0); G8_STA(G8_SA(1, 1), a1, sg1, 1);
;             G8_WAIT_V(8); G8_WAIT_L(0); G8_BAR; G8_MMA(0, 0, At, B0); G8_MMA(0, 1, At, B1); G8_BAR; G8_SCHED;
;             G8_LDA(At, 0, 1); G8_STB(G8_SB(0, 0), b2, sg2, 0); G8_STB(G8_SB(0, 1), b2, sg2, 1); G8_STA(G8_SA(0, 0), a2, sg2, 0);
;             G8_WAIT_V(8); G8_WAIT_L(0); G8_BAR; G8_MMA(1, 0, At, B0); G8_MMA(1, 1, At, B1); G8_BAR; G8_SCHED;
.LBB0_707:
	s_barrier
	ds_read_b128 v[68:71], v230
	ds_read_b128 v[72:75], v230 offset:1024
	ds_read_b128 v[76:79], v230 offset:2048
	ds_read_b128 v[138:141], v230 offset:3072
	ds_read_b128 v[142:145], v231
	ds_read_b128 v[154:157], v231 offset:1024
	ds_read_b128 v[158:161], v231 offset:2048
	ds_read_b128 v[162:165], v231 offset:3072
	s_add_u32 s65, s74, s76
	s_addc_u32 s66, s75, s77
	s_add_u32 s65, s65, 0x800000
	s_addc_u32 s66, s66, 0
	s_cmp_eq_u32 s76, 0x7800000
	s_cselect_b32 s67, s18, s66
	s_cselect_b32 s66, s19, s65
	s_cselect_b32 s79, s61, s29
	s_cselect_b32 s78, s63, s28
	v_lshl_add_u64 v[80:81], v[66:67], 0, s[76:77]
	s_mov_b64 s[80:81], 0x401000
	v_lshl_add_u64 v[198:199], v[80:81], 0, s[80:81]
	s_add_i32 m0, s25, 0xc000
	ds_read_b128 v[166:169], v232
	ds_read_b128 v[170:173], v232 offset:1024
	ds_read_b128 v[174:177], v232 offset:2048
	ds_read_b128 v[178:181], v232 offset:3072
	ds_read_b128 v[182:185], v232 offset:4096
	ds_read_b128 v[186:189], v232 offset:5120
	ds_read_b128 v[190:193], v232 offset:6144
	ds_read_b128 v[194:197], v232 offset:7168
	global_load_lds_dwordx4 v[198:199], off
	v_lshl_add_u64 v[80:81], v[80:81], 0, s[54:55]
	s_add_i32 m0, s25, 0xe000
	s_nop 0
	global_load_lds_dwordx4 v[80:81], off
	s_waitcnt vmcnt(8)
	s_waitcnt lgkmcnt(0)
	s_barrier
	s_waitcnt lgkmcnt(0)
	v_mfma_f32_16x16x32_bf16 v[150:153], v[68:71], v[166:169], v[150:153]
	v_mfma_f32_16x16x32_bf16 v[146:149], v[76:79], v[166:169], v[146:149]
	v_mfma_f32_16x16x32_bf16 v[126:129], v[68:71], v[174:177], v[126:129]
	v_mfma_f32_16x16x32_bf16 v[122:125], v[76:79], v[174:177], v[122:125]
	v_mfma_f32_16x16x32_bf16 v[110:113], v[68:71], v[182:185], v[110:113]
	v_mfma_f32_16x16x32_bf16 v[106:109], v[76:79], v[182:185], v[106:109]
	v_mfma_f32_16x16x32_bf16 v[94:97], v[68:71], v[190:193], v[94:97]
	v_mfma_f32_16x16x32_bf16 v[90:93], v[76:79], v[190:193], v[90:93]
	v_mfma_f32_16x16x32_bf16 v[150:153], v[72:75], v[170:173], v[150:153]
	v_mfma_f32_16x16x32_bf16 v[146:149], v[138:141], v[170:173], v[146:149]
	v_mfma_f32_16x16x32_bf16 v[126:129], v[72:75], v[178:181], v[126:129]
	v_mfma_f32_16x16x32_bf16 v[122:125], v[138:141], v[178:181], v[122:125]
	v_mfma_f32_16x16x32_bf16 v[110:113], v[72:75], v[186:189], v[110:113]
	v_mfma_f32_16x16x32_bf16 v[106:109], v[138:141], v[186:189], v[106:109]
	v_mfma_f32_16x16x32_bf16 v[94:97], v[72:75], v[194:197], v[94:97]
	v_mfma_f32_16x16x32_bf16 v[90:93], v[138:141], v[194:197], v[90:93]
	v_mfma_f32_16x16x32_bf16 v[134:137], v[142:145], v[166:169], v[134:137]
	v_mfma_f32_16x16x32_bf16 v[130:133], v[158:161], v[166:169], v[130:133]
	v_mfma_f32_16x16x32_bf16 v[118:121], v[142:145], v[174:177], v[118:121]
	v_mfma_f32_16x16x32_bf16 v[114:117], v[158:161], v[174:177], v[114:117]
	v_mfma_f32_16x16x32_bf16 v[102:105], v[142:145], v[182:185], v[102:105]
	v_mfma_f32_16x16x32_bf16 v[98:101], v[158:161], v[182:185], v[98:101]
	v_mfma_f32_16x16x32_bf16 v[86:89], v[142:145], v[190:193], v[86:89]
	v_mfma_f32_16x16x32_bf16 v[80:83], v[158:161], v[190:193], v[82:85]
	v_mfma_f32_16x16x32_bf16 v[134:137], v[154:157], v[170:173], v[134:137]
	v_mfma_f32_16x16x32_bf16 v[130:133], v[162:165], v[170:173], v[130:133]
	v_mfma_f32_16x16x32_bf16 v[118:121], v[154:157], v[178:181], v[118:121]
	v_mfma_f32_16x16x32_bf16 v[114:117], v[162:165], v[178:181], v[114:117]
	v_mfma_f32_16x16x32_bf16 v[102:105], v[154:157], v[186:189], v[102:105]
	v_mfma_f32_16x16x32_bf16 v[98:101], v[162:165], v[186:189], v[98:101]
	v_mfma_f32_16x16x32_bf16 v[86:89], v[154:157], v[194:197], v[86:89]
	v_mfma_f32_16x16x32_bf16 v[80:83], v[162:165], v[194:197], v[80:83]
	s_barrier
	s_add_i32 s65, s50, s24
	v_lshl_add_u64 v[198:199], s[78:79], 0, v[202:203]
	s_mov_b32 m0, s65
	ds_read_b128 v[166:169], v232 offset:16384
	ds_read_b128 v[170:173], v232 offset:17408
	ds_read_b128 v[174:177], v232 offset:18432
	ds_read_b128 v[178:181], v232 offset:19456
	ds_read_b128 v[182:185], v232 offset:20480
	ds_read_b128 v[186:189], v232 offset:21504
	ds_read_b128 v[190:193], v232 offset:22528
	ds_read_b128 v[194:197], v232 offset:23552
	global_load_lds_dwordx4 v[198:199], off
	v_lshl_add_u64 v[84:85], v[198:199], 0, s[6:7]
	s_add_i32 m0, s65, 0x2000
	s_add_i32 s65, s51, s24
	global_load_lds_dwordx4 v[84:85], off
	v_lshl_add_u64 v[84:85], v[198:199], 0, s[8:9]
	s_mov_b32 m0, s65
	v_lshl_add_u64 v[200:201], s[66:67], 0, v[204:205]
	global_load_lds_dwordx4 v[84:85], off
	v_lshl_add_u64 v[84:85], v[198:199], 0, s[10:11]
	s_add_i32 m0, s65, 0x2000
	s_nop 0
	global_load_lds_dwordx4 v[84:85], off
	s_mov_b32 m0, s25
	v_lshl_add_u64 v[84:85], v[200:201], 0, s[12:13]
	global_load_lds_dwordx4 v[200:201], off
	s_mov_b32 m0, s26
	s_nop 0
	global_load_lds_dwordx4 v[84:85], off
	s_waitcnt vmcnt(8)
	s_waitcnt lgkmcnt(0)
	s_barrier
	s_waitcnt lgkmcnt(0)
	v_mfma_f32_16x16x32_bf16 v[62:65], v[68:71], v[166:169], v[62:65]
	v_mfma_f32_16x16x32_bf16 v[58:61], v[76:79], v[166:169], v[58:61]
	v_mfma_f32_16x16x32_bf16 v[46:49], v[68:71], v[174:177], v[46:49]
	v_mfma_f32_16x16x32_bf16 v[42:45], v[76:79], v[174:177], v[42:45]
	v_mfma_f32_16x16x32_bf16 v[30:33], v[68:71], v[182:185], v[30:33]
	v_mfma_f32_16x16x32_bf16 v[26:29], v[76:79], v[182:185], v[26:29]
	v_mfma_f32_16x16x32_bf16 v[14:17], v[68:71], v[190:193], v[14:17]
	v_mfma_f32_16x16x32_bf16 v[10:13], v[76:79], v[190:193], v[10:13]
	v_mfma_f32_16x16x32_bf16 v[62:65], v[72:75], v[170:173], v[62:65]
	v_mfma_f32_16x16x32_bf16 v[58:61], v[138:141], v[170:173], v[58:61]
	v_mfma_f32_16x16x32_bf16 v[46:49], v[72:75], v[178:181], v[46:49]
	v_mfma_f32_16x16x32_bf16 v[42:45], v[138:141], v[178:181], v[42:45]
	v_mfma_f32_16x16x32_bf16 v[30:33], v[72:75], v[186:189], v[30:33]
	v_mfma_f32_16x16x32_bf16 v[26:29], v[138:141], v[186:189], v[26:29]
	v_mfma_f32_16x16x32_bf16 v[14:17], v[72:75], v[194:197], v[14:17]
	v_mfma_f32_16x16x32_bf16 v[10:13], v[138:141], v[194:197], v[10:13]
	v_mfma_f32_16x16x32_bf16 v[54:57], v[142:145], v[166:169], v[54:57]
	v_mfma_f32_16x16x32_bf16 v[50:53], v[158:161], v[166:169], v[50:53]
	v_mfma_f32_16x16x32_bf16 v[38:41], v[142:145], v[174:177], v[38:41]
	v_mfma_f32_16x16x32_bf16 v[34:37], v[158:161], v[174:177], v[34:37]
	v_mfma_f32_16x16x32_bf16 v[22:25], v[142:145], v[182:185], v[22:25]
	v_mfma_f32_16x16x32_bf16 v[18:21], v[158:161], v[182:185], v[18:21]
	v_mfma_f32_16x16x32_bf16 v[6:9], v[142:145], v[190:193], v[6:9]
	v_mfma_f32_16x16x32_bf16 v[2:5], v[158:161], v[190:193], v[2:5]
	v_mfma_f32_16x16x32_bf16 v[54:57], v[154:157], v[170:173], v[54:57]
	v_mfma_f32_16x16x32_bf16 v[50:53], v[162:165], v[170:173], v[50:53]
	v_mfma_f32_16x16x32_bf16 v[38:41], v[154:157], v[178:181], v[38:41]
	v_mfma_f32_16x16x32_bf16 v[34:37], v[162:165], v[178:181], v[34:37]
	v_mfma_f32_16x16x32_bf16 v[22:25], v[154:157], v[186:189], v[22:25]
	v_mfma_f32_16x16x32_bf16 v[18:21], v[162:165], v[186:189], v[18:21]
	v_mfma_f32_16x16x32_bf16 v[6:9], v[154:157], v[194:197], v[6:9]
	v_mfma_f32_16x16x32_bf16 v[2:5], v[162:165], v[194:197], v[2:5]
; #define G8_STA(bufoff, ptr, sg, h) G8_STAGE1(bufoff, (ptr) + (h) * ((sg) ? hA1 : hA0), ((sg) ? voffA1 : voffA0), ((sg) ? r64A1 : r64A0))
; #define G8_STB(bufoff, ptr, sg, h) G8_STAGE1(bufoff, (ptr) + (h) * ((sg) ? hB1 : hB0), ((sg) ? voffB1 : voffB0), ((sg) ? r64B1 : r64B0))
; #define G8_LDA(dst, b, h) do { _Pragma("unroll") for (int m = 0; m < 4; ++m) _Pragma("unroll") for (int k = 0; k < 2; ++k) dst[m][k] = *(const LAS bf16x8*)(lds + G8_SA(b, h) + aoff + m * 2048 + k * 1024); } while (0)
; #define G8_LDB(dst, b, h) do { _Pragma("unroll") for (int n = 0; n < 2; ++n) _Pragma("unroll") for (int k = 0; k < 2; ++k) dst[n][k] = *(const LAS bf16x8*)(lds + G8_SB(b, h) + boff + n * 2048 + k * 1024); } while (0)
; #define G8_MMA(ai, bj, At, Bt) do { __builtin_amdgcn_s_setprio(1); _Pragma("unroll") for (int m = 0; m < 4; ++m) _Pragma("unroll") for (int n = 0; n < 2; ++n) _Pragma("unroll") for (int k = 0; k < 2; ++k) \
;         acc[ai][bj][m][n] = __builtin_amdgcn_mfma_f32_16x16x32_bf16(Bt[n][k], At[m][k], acc[ai][bj][m][n], 0, 0, 0); __builtin_amdgcn_s_setprio(0); } while (0)
; #define G8_WAIT_V(n) asm volatile("s_waitcnt vmcnt(" #n ")" ::: "memory")
; #define G8_WAIT_L(n) asm volatile("s_waitcnt lgkmcnt(" #n ")" ::: "memory")
; #define G8_BAR __builtin_amdgcn_s_barrier()
; #define G8_SCHED __builtin_amdgcn_sched_barrier(0)
; template <class P>
; __device__ __forceinline__ void gemm_phase(LAS unsigned char* lds, const P& p, const int G, const int c) {
;     ...
;             G8_LDB(B0, 1, 0); G8_LDB(B1, 1, 1); G8_SCHED; G8_LDA(At, 1, 0); G8_STA(G8_SA(0, 1), a2, sg2, 1);
;             G8_WAIT_V(8); G8_WAIT_L(0); G8_BAR; G8_MMA(0, 0, At, B0); G8_MMA(0, 1, At, B1); G8_BAR; G8_SCHED;
;             G8_LDA(At, 1, 1); G8_STB(G8_SB(1, 0), b3, sg2, 0); G8_STB(G8_SB(1, 1), b3, sg2, 1); G8_STA(G8_SA(1, 0), a3, sg2, 0);
;             G8_WAIT_V(8); G8_WAIT_L(0); G8_BAR; G8_MMA(1, 0, At, B0); G8_MMA(1, 1, At, B1); G8_BAR; G8_SCHED;
;         }
.Lmid_707:
	s_barrier
	s_add_i32 s65, 0, 0x18000
	v_add_u32_e32 v84, s65, v229
	s_add_i32 s66, 0, 0x1c000
	ds_read_b128 v[68:71], v84
	ds_read_b128 v[72:75], v84 offset:1024
	ds_read_b128 v[76:79], v84 offset:2048
	ds_read_b128 v[138:141], v84 offset:3072
	v_add_u32_e32 v84, s66, v229
	ds_read_b128 v[142:145], v84
	ds_read_b128 v[154:157], v84 offset:1024
	ds_read_b128 v[158:161], v84 offset:2048
	ds_read_b128 v[162:165], v84 offset:3072
	s_mov_b32 m0, s27
	v_lshl_add_u64 v[84:85], v[200:201], 0, s[14:15]
	ds_read_b128 v[166:169], v232 offset:32768
	ds_read_b128 v[170:173], v232 offset:33792
	ds_read_b128 v[174:177], v232 offset:34816
	ds_read_b128 v[178:181], v232 offset:35840
	ds_read_b128 v[182:185], v232 offset:36864
	ds_read_b128 v[186:189], v232 offset:37888
	ds_read_b128 v[190:193], v232 offset:38912
	ds_read_b128 v[194:197], v232 offset:39936
	global_load_lds_dwordx4 v[84:85], off
	v_lshl_add_u64 v[84:85], v[200:201], 0, s[16:17]
	s_mov_b32 m0, s31
	s_nop 0
	global_load_lds_dwordx4 v[84:85], off
	s_waitcnt vmcnt(8)
	s_waitcnt lgkmcnt(0)
	s_barrier
	s_waitcnt lgkmcnt(0)
	v_mfma_f32_16x16x32_bf16 v[150:153], v[68:71], v[166:169], v[150:153]
	v_mfma_f32_16x16x32_bf16 v[146:149], v[76:79], v[166:169], v[146:149]
	v_mfma_f32_16x16x32_bf16 v[126:129], v[68:71], v[174:177], v[126:129]
	v_mfma_f32_16x16x32_bf16 v[122:125], v[76:79], v[174:177], v[122:125]
	v_mfma_f32_16x16x32_bf16 v[110:113], v[68:71], v[182:185], v[110:113]
	v_mfma_f32_16x16x32_bf16 v[106:109], v[76:79], v[182:185], v[106:109]
	v_mfma_f32_16x16x32_bf16 v[94:97], v[68:71], v[190:193], v[94:97]
	v_mfma_f32_16x16x32_bf16 v[90:93], v[76:79], v[190:193], v[90:93]
	v_mfma_f32_16x16x32_bf16 v[150:153], v[72:75], v[170:173], v[150:153]
	v_mfma_f32_16x16x32_bf16 v[146:149], v[138:141], v[170:173], v[146:149]
	v_mfma_f32_16x16x32_bf16 v[126:129], v[72:75], v[178:181], v[126:129]
	v_mfma_f32_16x16x32_bf16 v[122:125], v[138:141], v[178:181], v[122:125]
	v_mfma_f32_16x16x32_bf16 v[110:113], v[72:75], v[186:189], v[110:113]
	v_mfma_f32_16x16x32_bf16 v[106:109], v[138:141], v[186:189], v[106:109]
	v_mfma_f32_16x16x32_bf16 v[94:97], v[72:75], v[194:197], v[94:97]
	v_mfma_f32_16x16x32_bf16 v[90:93], v[138:141], v[194:197], v[90:93]
	v_mfma_f32_16x16x32_bf16 v[134:137], v[142:145], v[166:169], v[134:137]
	v_mfma_f32_16x16x32_bf16 v[130:133], v[158:161], v[166:169], v[130:133]
	v_mfma_f32_16x16x32_bf16 v[118:121], v[142:145], v[174:177], v[118:121]
	v_mfma_f32_16x16x32_bf16 v[114:117], v[158:161], v[174:177], v[114:117]
	v_mfma_f32_16x16x32_bf16 v[102:105], v[142:145], v[182:185], v[102:105]
	v_mfma_f32_16x16x32_bf16 v[98:101], v[158:161], v[182:185], v[98:101]
	v_mfma_f32_16x16x32_bf16 v[84:87], v[142:145], v[190:193], v[86:89]
	v_mfma_f32_16x16x32_bf16 v[80:83], v[158:161], v[190:193], v[80:83]
	v_mfma_f32_16x16x32_bf16 v[134:137], v[154:157], v[170:173], v[134:137]
	v_mfma_f32_16x16x32_bf16 v[130:133], v[162:165], v[170:173], v[130:133]
	v_mfma_f32_16x16x32_bf16 v[118:121], v[154:157], v[178:181], v[118:121]
	v_mfma_f32_16x16x32_bf16 v[114:117], v[162:165], v[178:181], v[114:117]
	v_mfma_f32_16x16x32_bf16 v[102:105], v[154:157], v[186:189], v[102:105]
	v_mfma_f32_16x16x32_bf16 v[98:101], v[162:165], v[186:189], v[98:101]
	v_mfma_f32_16x16x32_bf16 v[86:89], v[154:157], v[194:197], v[84:87]
	v_mfma_f32_16x16x32_bf16 v[82:85], v[162:165], v[194:197], v[80:83]
	s_barrier
	s_add_i32 s65, s65, s24
	v_lshl_add_u64 v[80:81], v[198:199], 0, s[36:37]
	s_mov_b32 m0, s65
	ds_read_b128 v[166:169], v232 offset:49152
	ds_read_b128 v[170:173], v232 offset:50176
	ds_read_b128 v[174:177], v232 offset:51200
	ds_read_b128 v[178:181], v232 offset:52224
	ds_read_b128 v[182:185], v232 offset:53248
	ds_read_b128 v[186:189], v232 offset:54272
	ds_read_b128 v[190:193], v232 offset:55296
	ds_read_b128 v[194:197], v232 offset:56320
	global_load_lds_dwordx4 v[80:81], off
	v_lshl_add_u64 v[80:81], v[198:199], 0, s[38:39]
	s_add_i32 m0, s65, 0x2000
	s_add_i32 s65, s66, s24
	global_load_lds_dwordx4 v[80:81], off
	v_lshl_add_u64 v[80:81], v[198:199], 0, s[44:45]
	s_mov_b32 m0, s65
	s_nop 0
	global_load_lds_dwordx4 v[80:81], off
	v_lshl_add_u64 v[80:81], v[198:199], 0, s[48:49]
	s_add_i32 m0, s65, 0x2000
	s_nop 0
	global_load_lds_dwordx4 v[80:81], off
	v_lshl_add_u64 v[80:81], v[200:201], 0, s[40:41]
	s_mov_b32 m0, s46
	s_nop 0
	global_load_lds_dwordx4 v[80:81], off
	v_lshl_add_u64 v[80:81], v[200:201], 0, s[42:43]
	s_mov_b32 m0, s47
	s_nop 0
	global_load_lds_dwordx4 v[80:81], off
	s_waitcnt vmcnt(8)
	s_waitcnt lgkmcnt(0)
	s_barrier
	s_waitcnt lgkmcnt(0)
	v_mfma_f32_16x16x32_bf16 v[62:65], v[68:71], v[166:169], v[62:65]
	v_mfma_f32_16x16x32_bf16 v[58:61], v[76:79], v[166:169], v[58:61]
	v_mfma_f32_16x16x32_bf16 v[46:49], v[68:71], v[174:177], v[46:49]
	v_mfma_f32_16x16x32_bf16 v[42:45], v[76:79], v[174:177], v[42:45]
	v_mfma_f32_16x16x32_bf16 v[30:33], v[68:71], v[182:185], v[30:33]
	v_mfma_f32_16x16x32_bf16 v[26:29], v[76:79], v[182:185], v[26:29]
	v_mfma_f32_16x16x32_bf16 v[14:17], v[68:71], v[190:193], v[14:17]
	v_mfma_f32_16x16x32_bf16 v[10:13], v[76:79], v[190:193], v[10:13]
	v_mfma_f32_16x16x32_bf16 v[62:65], v[72:75], v[170:173], v[62:65]
	v_mfma_f32_16x16x32_bf16 v[58:61], v[138:141], v[170:173], v[58:61]
	v_mfma_f32_16x16x32_bf16 v[46:49], v[72:75], v[178:181], v[46:49]
	v_mfma_f32_16x16x32_bf16 v[42:45], v[138:141], v[178:181], v[42:45]
	v_mfma_f32_16x16x32_bf16 v[30:33], v[72:75], v[186:189], v[30:33]
	v_mfma_f32_16x16x32_bf16 v[26:29], v[138:141], v[186:189], v[26:29]
	v_mfma_f32_16x16x32_bf16 v[14:17], v[72:75], v[194:197], v[14:17]
	v_mfma_f32_16x16x32_bf16 v[10:13], v[138:141], v[194:197], v[10:13]
	v_mfma_f32_16x16x32_bf16 v[54:57], v[142:145], v[166:169], v[54:57]
	v_mfma_f32_16x16x32_bf16 v[50:53], v[158:161], v[166:169], v[50:53]
	v_mfma_f32_16x16x32_bf16 v[38:41], v[142:145], v[174:177], v[38:41]
	v_mfma_f32_16x16x32_bf16 v[34:37], v[158:161], v[174:177], v[34:37]
	v_mfma_f32_16x16x32_bf16 v[22:25], v[142:145], v[182:185], v[22:25]
	v_mfma_f32_16x16x32_bf16 v[18:21], v[158:161], v[182:185], v[18:21]
	v_mfma_f32_16x16x32_bf16 v[6:9], v[142:145], v[190:193], v[6:9]
	v_mfma_f32_16x16x32_bf16 v[2:5], v[158:161], v[190:193], v[2:5]
	v_mfma_f32_16x16x32_bf16 v[54:57], v[154:157], v[170:173], v[54:57]
	v_mfma_f32_16x16x32_bf16 v[50:53], v[162:165], v[170:173], v[50:53]
	v_mfma_f32_16x16x32_bf16 v[38:41], v[154:157], v[178:181], v[38:41]
	v_mfma_f32_16x16x32_bf16 v[34:37], v[162:165], v[178:181], v[34:37]
	v_mfma_f32_16x16x32_bf16 v[22:25], v[154:157], v[186:189], v[22:25]
	v_mfma_f32_16x16x32_bf16 v[18:21], v[162:165], v[186:189], v[18:21]
	v_mfma_f32_16x16x32_bf16 v[6:9], v[154:157], v[194:197], v[6:9]
	v_mfma_f32_16x16x32_bf16 v[2:5], v[162:165], v[194:197], v[2:5]
	s_add_i32 s64, s64, 2
	s_add_u32 s28, s28, 0x80000
	s_addc_u32 s29, s29, 0
	s_add_u32 s76, s76, 0x800000
	s_addc_u32 s77, s77, 0
	s_cmp_gt_u32 s64, 29
	s_cbranch_scc0 .LBB0_707
	s_barrier
	s_and_b64 vcc, exec, s[52:53]
	s_cbranch_vccz .LBB0_710
	s_barrier

; #define G8_STA(bufoff, ptr, sg, h) G8_STAGE1(bufoff, (ptr) + (h) * ((sg) ? hA1 : hA0), ((sg) ? voffA1 : voffA0), ((sg) ? r64A1 : r64A0))
; #define G8_STB(bufoff, ptr, sg, h) G8_STAGE1(bufoff, (ptr) + (h) * ((sg) ? hB1 : hB0), ((sg) ? voffB1 : voffB0), ((sg) ? r64B1 : r64B0))
; #define G8_LDA(dst, b, h) do { _Pragma("unroll") for (int m = 0; m < 4; ++m) _Pragma("unroll") for (int k = 0; k < 2; ++k) dst[m][k] = *(const LAS bf16x8*)(lds + G8_SA(b, h) + aoff + m * 2048 + k * 1024); } while (0)
; #define G8_LDB(dst, b, h) do { _Pragma("unroll") for (int n = 0; n < 2; ++n) _Pragma("unroll") for (int k = 0; k < 2; ++k) dst[n][k] = *(const LAS bf16x8*)(lds + G8_SB(b, h) + boff + n * 2048 + k * 1024); } while (0)
; #define G8_MMA(ai, bj, At, Bt) do { __builtin_amdgcn_s_setprio(1); _Pragma("unroll") for (int m = 0; m < 4; ++m) _Pragma("unroll") for (int n = 0; n < 2; ++n) _Pragma("unroll") for (int k = 0; k < 2; ++k) \
;         acc[ai][bj][m][n] = __builtin_amdgcn_mfma_f32_16x16x32_bf16(Bt[n][k], At[m][k], acc[ai][bj][m][n], 0, 0, 0); __builtin_amdgcn_s_setprio(0); } while (0)
; #define G8_BAR __builtin_amdgcn_s_barrier()
; template <class P>
; __device__ __forceinline__ void gemm_phase(LAS unsigned char* lds, const P& p, const int G, const int c) {
;     ...
;         for (int t = 0; t < nt; t += 2) {
;             const bool last = (t == nt - 2);
;             const bool sg1 = (NS > 1) && (t + 1 >= nt0);
;             const bool sg2 = (NS > 1) && !last && (t + 2 >= nt0);
;             const char* a1 = sg1 ? cA1 + (long)(t + 1 - nt0) * ksA1 : cA0 + (long)(t + 1) * ksA0;
;             const char* a2 = last ? nA0 : (sg2 ? cA1 + (long)(t + 2 - nt0) * ksA1 : cA0 + (long)(t + 2) * ksA0);
;             const char* b2 = last ? nB0 : (sg2 ? cB1 + (long)(t + 2 - nt0) * ksB1 : cB0 + (long)(t + 2) * ksB0);
;             const char* a3 = a2 + (sg2 ? ksA1 : ksA0); const char* b3 = b2 + (sg2 ? ksB1 : ksB0);
;             G8_LDB(B0, 0, 0); G8_LDB(B1, 0, 1); G8_SCHED; G8_LDA(At, 0, 0); G8_STA(G8_SA(1, 1), a1, sg1, 1);
;             G8_WAIT_V(8); G8_WAIT_L(0); G8_BAR; G8_MMA(0, 0, At, B0); G8_MMA(0, 1, At, B1); G8_BAR; G8_SCHED;
;             G8_LDA(At, 0, 1); G8_STB(G8_SB(0, 0), b2, sg2, 0); G8_STB(G8_SB(0, 1), b2, sg2, 1); G8_STA(G8_SA(0, 0), a2, sg2, 0);
;             G8_WAIT_V(8); G8_WAIT_L(0); G8_BAR; G8_MMA(1, 0, At, B0); G8_MMA(1, 1, At, B1); G8_BAR; G8_SCHED;
.LBB0_770:
	s_barrier
	ds_read_b128 v[130:133], v158
	ds_read_b128 v[134:137], v158 offset:1024
	ds_read_b128 v[138:141], v158 offset:2048
	ds_read_b128 v[162:165], v158 offset:3072
	ds_read_b128 v[166:169], v159
	ds_read_b128 v[170:173], v159 offset:1024
	ds_read_b128 v[174:177], v159 offset:2048
	ds_read_b128 v[178:181], v159 offset:3072
	s_add_u32 s77, s70, s72
	s_addc_u32 s78, s71, s73
	s_add_u32 s77, s77, 0x800000
	s_addc_u32 s78, s78, 0
	s_cmp_eq_u32 s72, 0x7800000
	s_cselect_b32 s79, s18, s78
	s_cselect_b32 s78, s19, s77
	s_cselect_b32 s81, s57, s29
	s_cselect_b32 s80, s59, s28
	v_lshl_add_u64 v[142:143], v[128:129], 0, s[72:73]
	v_lshl_add_u64 v[154:155], v[142:143], 0, s[40:41]
	s_add_i32 m0, s27, 0xc000
	ds_read_b128 v[182:185], v160
	ds_read_b128 v[186:189], v160 offset:1024
	ds_read_b128 v[190:193], v160 offset:2048
	ds_read_b128 v[194:197], v160 offset:3072
	ds_read_b128 v[198:201], v160 offset:4096
	ds_read_b128 v[202:205], v160 offset:5120
	ds_read_b128 v[210:213], v160 offset:6144
	ds_read_b128 v[214:217], v160 offset:7168
	global_load_lds_dwordx4 v[154:155], off
	v_lshl_add_u64 v[142:143], v[142:143], 0, s[42:43]
	s_add_i32 m0, s27, 0xe000
	s_nop 0
	global_load_lds_dwordx4 v[142:143], off
	s_waitcnt vmcnt(8)
	s_waitcnt lgkmcnt(0)
	s_barrier
	s_waitcnt lgkmcnt(0)
	v_mfma_f32_16x16x32_bf16 v[120:123], v[130:133], v[182:185], v[120:123]
	v_mfma_f32_16x16x32_bf16 v[124:127], v[138:141], v[182:185], v[124:127]
	v_mfma_f32_16x16x32_bf16 v[112:115], v[130:133], v[190:193], v[112:115]
	v_mfma_f32_16x16x32_bf16 v[116:119], v[138:141], v[190:193], v[116:119]
	v_mfma_f32_16x16x32_bf16 v[100:103], v[130:133], v[198:201], v[100:103]
	v_mfma_f32_16x16x32_bf16 v[108:111], v[138:141], v[198:201], v[108:111]
	v_mfma_f32_16x16x32_bf16 v[84:87], v[130:133], v[210:213], v[84:87]
	v_mfma_f32_16x16x32_bf16 v[72:75], v[138:141], v[210:213], v[72:75]
	v_mfma_f32_16x16x32_bf16 v[120:123], v[134:137], v[186:189], v[120:123]
	v_mfma_f32_16x16x32_bf16 v[124:127], v[162:165], v[186:189], v[124:127]
	v_mfma_f32_16x16x32_bf16 v[112:115], v[134:137], v[194:197], v[112:115]
	v_mfma_f32_16x16x32_bf16 v[116:119], v[162:165], v[194:197], v[116:119]
	v_mfma_f32_16x16x32_bf16 v[100:103], v[134:137], v[202:205], v[100:103]
	v_mfma_f32_16x16x32_bf16 v[108:111], v[162:165], v[202:205], v[108:111]
	v_mfma_f32_16x16x32_bf16 v[84:87], v[134:137], v[214:217], v[84:87]
	v_mfma_f32_16x16x32_bf16 v[72:75], v[162:165], v[214:217], v[72:75]
	v_mfma_f32_16x16x32_bf16 v[104:107], v[166:169], v[182:185], v[104:107]
	v_mfma_f32_16x16x32_bf16 v[92:95], v[174:177], v[182:185], v[92:95]
	v_mfma_f32_16x16x32_bf16 v[96:99], v[166:169], v[190:193], v[96:99]
	v_mfma_f32_16x16x32_bf16 v[80:83], v[174:177], v[190:193], v[80:83]
	v_mfma_f32_16x16x32_bf16 v[88:91], v[166:169], v[198:201], v[88:91]
	v_mfma_f32_16x16x32_bf16 v[76:79], v[174:177], v[198:201], v[76:79]
	v_mfma_f32_16x16x32_bf16 v[68:71], v[166:169], v[210:213], v[68:71]
	v_mfma_f32_16x16x32_bf16 v[64:67], v[174:177], v[210:213], v[64:67]
	v_mfma_f32_16x16x32_bf16 v[104:107], v[170:173], v[186:189], v[104:107]
	v_mfma_f32_16x16x32_bf16 v[92:95], v[178:181], v[186:189], v[92:95]
	v_mfma_f32_16x16x32_bf16 v[96:99], v[170:173], v[194:197], v[96:99]
	v_mfma_f32_16x16x32_bf16 v[80:83], v[178:181], v[194:197], v[80:83]
	v_mfma_f32_16x16x32_bf16 v[88:91], v[170:173], v[202:205], v[88:91]
	v_mfma_f32_16x16x32_bf16 v[76:79], v[178:181], v[202:205], v[76:79]
	v_mfma_f32_16x16x32_bf16 v[68:71], v[170:173], v[214:217], v[68:71]
	v_mfma_f32_16x16x32_bf16 v[64:67], v[178:181], v[214:217], v[64:67]
	s_barrier
	s_add_i32 s77, s30, s26
	v_lshl_add_u64 v[142:143], s[80:81], 0, v[144:145]
	s_mov_b32 m0, s77
	ds_read_b128 v[182:185], v160 offset:16384
	ds_read_b128 v[186:189], v160 offset:17408
	ds_read_b128 v[190:193], v160 offset:18432
	ds_read_b128 v[194:197], v160 offset:19456
	ds_read_b128 v[198:201], v160 offset:20480
	ds_read_b128 v[202:205], v160 offset:21504
	ds_read_b128 v[210:213], v160 offset:22528
	ds_read_b128 v[214:217], v160 offset:23552
	global_load_lds_dwordx4 v[142:143], off
	v_lshl_add_u64 v[154:155], v[142:143], 0, s[4:5]
	s_add_i32 m0, s77, 0x2000
	s_add_i32 s77, s74, s26
	global_load_lds_dwordx4 v[154:155], off
	v_lshl_add_u64 v[154:155], v[142:143], 0, s[6:7]
	s_mov_b32 m0, s77
	s_nop 0
	global_load_lds_dwordx4 v[154:155], off
	v_lshl_add_u64 v[154:155], v[142:143], 0, s[8:9]
	s_add_i32 m0, s77, 0x2000
	s_nop 0
	global_load_lds_dwordx4 v[154:155], off
	v_lshl_add_u64 v[154:155], s[78:79], 0, v[146:147]
	s_mov_b32 m0, s27
	v_lshl_add_u64 v[206:207], v[154:155], 0, s[4:5]
	global_load_lds_dwordx4 v[154:155], off
	s_mov_b32 m0, s31
	s_nop 0
	global_load_lds_dwordx4 v[206:207], off
	s_waitcnt vmcnt(8)
	s_waitcnt lgkmcnt(0)
	s_barrier
	s_waitcnt lgkmcnt(0)
	v_mfma_f32_16x16x32_bf16 v[60:63], v[130:133], v[182:185], v[60:63]
	v_mfma_f32_16x16x32_bf16 v[56:59], v[138:141], v[182:185], v[56:59]
	v_mfma_f32_16x16x32_bf16 v[52:55], v[130:133], v[190:193], v[52:55]
	v_mfma_f32_16x16x32_bf16 v[44:47], v[138:141], v[190:193], v[44:47]
	v_mfma_f32_16x16x32_bf16 v[36:39], v[130:133], v[198:201], v[36:39]
	v_mfma_f32_16x16x32_bf16 v[28:31], v[138:141], v[198:201], v[28:31]
	v_mfma_f32_16x16x32_bf16 v[20:23], v[130:133], v[210:213], v[20:23]
	v_mfma_f32_16x16x32_bf16 v[12:15], v[138:141], v[210:213], v[12:15]
	v_mfma_f32_16x16x32_bf16 v[60:63], v[134:137], v[186:189], v[60:63]
	v_mfma_f32_16x16x32_bf16 v[56:59], v[162:165], v[186:189], v[56:59]
	v_mfma_f32_16x16x32_bf16 v[52:55], v[134:137], v[194:197], v[52:55]
	v_mfma_f32_16x16x32_bf16 v[44:47], v[162:165], v[194:197], v[44:47]
	v_mfma_f32_16x16x32_bf16 v[36:39], v[134:137], v[202:205], v[36:39]
	v_mfma_f32_16x16x32_bf16 v[28:31], v[162:165], v[202:205], v[28:31]
	v_mfma_f32_16x16x32_bf16 v[20:23], v[134:137], v[214:217], v[20:23]
	v_mfma_f32_16x16x32_bf16 v[12:15], v[162:165], v[214:217], v[12:15]
	v_mfma_f32_16x16x32_bf16 v[48:51], v[166:169], v[182:185], v[48:51]
	v_mfma_f32_16x16x32_bf16 v[40:43], v[174:177], v[182:185], v[40:43]
	v_mfma_f32_16x16x32_bf16 v[32:35], v[166:169], v[190:193], v[32:35]
	v_mfma_f32_16x16x32_bf16 v[24:27], v[174:177], v[190:193], v[24:27]
	v_mfma_f32_16x16x32_bf16 v[16:19], v[166:169], v[198:201], v[16:19]
	v_mfma_f32_16x16x32_bf16 v[8:11], v[174:177], v[198:201], v[8:11]
	v_mfma_f32_16x16x32_bf16 v[4:7], v[166:169], v[210:213], v[4:7]
	v_mfma_f32_16x16x32_bf16 v[0:3], v[174:177], v[210:213], v[0:3]
	v_mfma_f32_16x16x32_bf16 v[48:51], v[170:173], v[186:189], v[48:51]
	v_mfma_f32_16x16x32_bf16 v[40:43], v[178:181], v[186:189], v[40:43]
	v_mfma_f32_16x16x32_bf16 v[32:35], v[170:173], v[194:197], v[32:35]
	v_mfma_f32_16x16x32_bf16 v[24:27], v[178:181], v[194:197], v[24:27]
	v_mfma_f32_16x16x32_bf16 v[16:19], v[170:173], v[202:205], v[16:19]
	v_mfma_f32_16x16x32_bf16 v[8:11], v[178:181], v[202:205], v[8:11]
	v_mfma_f32_16x16x32_bf16 v[4:7], v[170:173], v[214:217], v[4:7]
	v_mfma_f32_16x16x32_bf16 v[0:3], v[178:181], v[214:217], v[0:3]
; #define G8_STA(bufoff, ptr, sg, h) G8_STAGE1(bufoff, (ptr) + (h) * ((sg) ? hA1 : hA0), ((sg) ? voffA1 : voffA0), ((sg) ? r64A1 : r64A0))
; #define G8_STB(bufoff, ptr, sg, h) G8_STAGE1(bufoff, (ptr) + (h) * ((sg) ? hB1 : hB0), ((sg) ? voffB1 : voffB0), ((sg) ? r64B1 : r64B0))
; #define G8_LDA(dst, b, h) do { _Pragma("unroll") for (int m = 0; m < 4; ++m) _Pragma("unroll") for (int k = 0; k < 2; ++k) dst[m][k] = *(const LAS bf16x8*)(lds + G8_SA(b, h) + aoff + m * 2048 + k * 1024); } while (0)
; #define G8_LDB(dst, b, h) do { _Pragma("unroll") for (int n = 0; n < 2; ++n) _Pragma("unroll") for (int k = 0; k < 2; ++k) dst[n][k] = *(const LAS bf16x8*)(lds + G8_SB(b, h) + boff + n * 2048 + k * 1024); } while (0)
; #define G8_MMA(ai, bj, At, Bt) do { __builtin_amdgcn_s_setprio(1); _Pragma("unroll") for (int m = 0; m < 4; ++m) _Pragma("unroll") for (int n = 0; n < 2; ++n) _Pragma("unroll") for (int k = 0; k < 2; ++k) \
;         acc[ai][bj][m][n] = __builtin_amdgcn_mfma_f32_16x16x32_bf16(Bt[n][k], At[m][k], acc[ai][bj][m][n], 0, 0, 0); __builtin_amdgcn_s_setprio(0); } while (0)
; #define G8_WAIT_V(n) asm volatile("s_waitcnt vmcnt(" #n ")" ::: "memory")
; #define G8_WAIT_L(n) asm volatile("s_waitcnt lgkmcnt(" #n ")" ::: "memory")
; #define G8_BAR __builtin_amdgcn_s_barrier()
; #define G8_SCHED __builtin_amdgcn_sched_barrier(0)
; template <class P>
; __device__ __forceinline__ void gemm_phase(LAS unsigned char* lds, const P& p, const int G, const int c) {
;     ...
;             G8_LDB(B0, 1, 0); G8_LDB(B1, 1, 1); G8_SCHED; G8_LDA(At, 1, 0); G8_STA(G8_SA(0, 1), a2, sg2, 1);
;             G8_WAIT_V(8); G8_WAIT_L(0); G8_BAR; G8_MMA(0, 0, At, B0); G8_MMA(0, 1, At, B1); G8_BAR; G8_SCHED;
;             G8_LDA(At, 1, 1); G8_STB(G8_SB(1, 0), b3, sg2, 0); G8_STB(G8_SB(1, 1), b3, sg2, 1); G8_STA(G8_SA(1, 0), a3, sg2, 0);
;             G8_WAIT_V(8); G8_WAIT_L(0); G8_BAR; G8_MMA(1, 0, At, B0); G8_MMA(1, 1, At, B1); G8_BAR; G8_SCHED;
;         }
.Lmid_770:
	s_barrier
	s_add_i32 s77, 0, 0x18000
	v_add_u32_e32 v161, s77, v156
	s_add_i32 s78, 0, 0x1c000
	ds_read_b128 v[130:133], v161
	ds_read_b128 v[134:137], v161 offset:1024
	ds_read_b128 v[138:141], v161 offset:2048
	ds_read_b128 v[162:165], v161 offset:3072
	v_add_u32_e32 v161, s78, v156
	ds_read_b128 v[166:169], v161
	ds_read_b128 v[170:173], v161 offset:1024
	ds_read_b128 v[174:177], v161 offset:2048
	ds_read_b128 v[178:181], v161 offset:3072
	s_mov_b32 m0, s33
	v_lshl_add_u64 v[206:207], v[154:155], 0, s[6:7]
	ds_read_b128 v[182:185], v160 offset:32768
	ds_read_b128 v[186:189], v160 offset:33792
	ds_read_b128 v[190:193], v160 offset:34816
	ds_read_b128 v[194:197], v160 offset:35840
	ds_read_b128 v[198:201], v160 offset:36864
	ds_read_b128 v[202:205], v160 offset:37888
	ds_read_b128 v[210:213], v160 offset:38912
	ds_read_b128 v[214:217], v160 offset:39936
	global_load_lds_dwordx4 v[206:207], off
	v_lshl_add_u64 v[206:207], v[154:155], 0, s[8:9]
	s_mov_b32 m0, s34
	s_nop 0
	global_load_lds_dwordx4 v[206:207], off
	s_waitcnt vmcnt(8)
	s_waitcnt lgkmcnt(0)
	s_barrier
	s_waitcnt lgkmcnt(0)
	v_mfma_f32_16x16x32_bf16 v[120:123], v[130:133], v[182:185], v[120:123]
	v_mfma_f32_16x16x32_bf16 v[124:127], v[138:141], v[182:185], v[124:127]
	v_mfma_f32_16x16x32_bf16 v[112:115], v[130:133], v[190:193], v[112:115]
	v_mfma_f32_16x16x32_bf16 v[116:119], v[138:141], v[190:193], v[116:119]
	v_mfma_f32_16x16x32_bf16 v[100:103], v[130:133], v[198:201], v[100:103]
	v_mfma_f32_16x16x32_bf16 v[108:111], v[138:141], v[198:201], v[108:111]
	v_mfma_f32_16x16x32_bf16 v[84:87], v[130:133], v[210:213], v[84:87]
	v_mfma_f32_16x16x32_bf16 v[72:75], v[138:141], v[210:213], v[72:75]
	v_mfma_f32_16x16x32_bf16 v[120:123], v[134:137], v[186:189], v[120:123]
	v_mfma_f32_16x16x32_bf16 v[124:127], v[162:165], v[186:189], v[124:127]
	v_mfma_f32_16x16x32_bf16 v[112:115], v[134:137], v[194:197], v[112:115]
	v_mfma_f32_16x16x32_bf16 v[116:119], v[162:165], v[194:197], v[116:119]
	v_mfma_f32_16x16x32_bf16 v[100:103], v[134:137], v[202:205], v[100:103]
	v_mfma_f32_16x16x32_bf16 v[108:111], v[162:165], v[202:205], v[108:111]
	v_mfma_f32_16x16x32_bf16 v[84:87], v[134:137], v[214:217], v[84:87]
	v_mfma_f32_16x16x32_bf16 v[72:75], v[162:165], v[214:217], v[72:75]
	v_mfma_f32_16x16x32_bf16 v[104:107], v[166:169], v[182:185], v[104:107]
	v_mfma_f32_16x16x32_bf16 v[92:95], v[174:177], v[182:185], v[92:95]
	v_mfma_f32_16x16x32_bf16 v[96:99], v[166:169], v[190:193], v[96:99]
	v_mfma_f32_16x16x32_bf16 v[80:83], v[174:177], v[190:193], v[80:83]
	v_mfma_f32_16x16x32_bf16 v[88:91], v[166:169], v[198:201], v[88:91]
	v_mfma_f32_16x16x32_bf16 v[76:79], v[174:177], v[198:201], v[76:79]
	v_mfma_f32_16x16x32_bf16 v[68:71], v[166:169], v[210:213], v[68:71]
	v_mfma_f32_16x16x32_bf16 v[64:67], v[174:177], v[210:213], v[64:67]
	v_mfma_f32_16x16x32_bf16 v[104:107], v[170:173], v[186:189], v[104:107]
	v_mfma_f32_16x16x32_bf16 v[92:95], v[178:181], v[186:189], v[92:95]
	v_mfma_f32_16x16x32_bf16 v[96:99], v[170:173], v[194:197], v[96:99]
	v_mfma_f32_16x16x32_bf16 v[80:83], v[178:181], v[194:197], v[80:83]
	v_mfma_f32_16x16x32_bf16 v[88:91], v[170:173], v[202:205], v[88:91]
	v_mfma_f32_16x16x32_bf16 v[76:79], v[178:181], v[202:205], v[76:79]
	v_mfma_f32_16x16x32_bf16 v[68:71], v[170:173], v[214:217], v[68:71]
	v_mfma_f32_16x16x32_bf16 v[64:67], v[178:181], v[214:217], v[64:67]
	s_barrier
	s_add_i32 s77, s77, s26
	v_lshl_add_u64 v[206:207], v[142:143], 0, s[12:13]
	s_mov_b32 m0, s77
	ds_read_b128 v[182:185], v160 offset:49152
	ds_read_b128 v[186:189], v160 offset:50176
	ds_read_b128 v[190:193], v160 offset:51200
	ds_read_b128 v[194:197], v160 offset:52224
	ds_read_b128 v[198:201], v160 offset:53248
	ds_read_b128 v[202:205], v160 offset:54272
	ds_read_b128 v[210:213], v160 offset:55296
	ds_read_b128 v[214:217], v160 offset:56320
	global_load_lds_dwordx4 v[206:207], off
	v_lshl_add_u64 v[206:207], v[142:143], 0, s[14:15]
	s_add_i32 m0, s77, 0x2000
	s_add_i32 s77, s78, s26
	global_load_lds_dwordx4 v[206:207], off
	v_lshl_add_u64 v[206:207], v[142:143], 0, s[22:23]
	s_mov_b32 m0, s77
	v_lshl_add_u64 v[142:143], v[142:143], 0, s[36:37]
	global_load_lds_dwordx4 v[206:207], off
	s_add_i32 m0, s77, 0x2000
	s_nop 0
	global_load_lds_dwordx4 v[142:143], off
	v_lshl_add_u64 v[142:143], v[154:155], 0, s[16:17]
	s_mov_b32 m0, s67
	s_nop 0
	global_load_lds_dwordx4 v[142:143], off
	v_lshl_add_u64 v[142:143], v[154:155], 0, s[20:21]
	s_mov_b32 m0, s69
	s_nop 0
	global_load_lds_dwordx4 v[142:143], off
	s_waitcnt vmcnt(8)
	s_waitcnt lgkmcnt(0)
	s_barrier
	s_waitcnt lgkmcnt(0)
	v_mfma_f32_16x16x32_bf16 v[60:63], v[130:133], v[182:185], v[60:63]
	v_mfma_f32_16x16x32_bf16 v[56:59], v[138:141], v[182:185], v[56:59]
	v_mfma_f32_16x16x32_bf16 v[52:55], v[130:133], v[190:193], v[52:55]
	v_mfma_f32_16x16x32_bf16 v[44:47], v[138:141], v[190:193], v[44:47]
	v_mfma_f32_16x16x32_bf16 v[36:39], v[130:133], v[198:201], v[36:39]
	v_mfma_f32_16x16x32_bf16 v[28:31], v[138:141], v[198:201], v[28:31]
	v_mfma_f32_16x16x32_bf16 v[20:23], v[130:133], v[210:213], v[20:23]
	v_mfma_f32_16x16x32_bf16 v[12:15], v[138:141], v[210:213], v[12:15]
	v_mfma_f32_16x16x32_bf16 v[60:63], v[134:137], v[186:189], v[60:63]
	v_mfma_f32_16x16x32_bf16 v[56:59], v[162:165], v[186:189], v[56:59]
	v_mfma_f32_16x16x32_bf16 v[52:55], v[134:137], v[194:197], v[52:55]
	v_mfma_f32_16x16x32_bf16 v[44:47], v[162:165], v[194:197], v[44:47]
	v_mfma_f32_16x16x32_bf16 v[36:39], v[134:137], v[202:205], v[36:39]
	v_mfma_f32_16x16x32_bf16 v[28:31], v[162:165], v[202:205], v[28:31]
	v_mfma_f32_16x16x32_bf16 v[20:23], v[134:137], v[214:217], v[20:23]
	v_mfma_f32_16x16x32_bf16 v[12:15], v[162:165], v[214:217], v[12:15]
	v_mfma_f32_16x16x32_bf16 v[48:51], v[166:169], v[182:185], v[48:51]
	v_mfma_f32_16x16x32_bf16 v[40:43], v[174:177], v[182:185], v[40:43]
	v_mfma_f32_16x16x32_bf16 v[32:35], v[166:169], v[190:193], v[32:35]
	v_mfma_f32_16x16x32_bf16 v[24:27], v[174:177], v[190:193], v[24:27]
	v_mfma_f32_16x16x32_bf16 v[16:19], v[166:169], v[198:201], v[16:19]
	v_mfma_f32_16x16x32_bf16 v[8:11], v[174:177], v[198:201], v[8:11]
	v_mfma_f32_16x16x32_bf16 v[4:7], v[166:169], v[210:213], v[4:7]
	v_mfma_f32_16x16x32_bf16 v[0:3], v[174:177], v[210:213], v[0:3]
	v_mfma_f32_16x16x32_bf16 v[48:51], v[170:173], v[186:189], v[48:51]
	v_mfma_f32_16x16x32_bf16 v[40:43], v[178:181], v[186:189], v[40:43]
	v_mfma_f32_16x16x32_bf16 v[32:35], v[170:173], v[194:197], v[32:35]
	v_mfma_f32_16x16x32_bf16 v[24:27], v[178:181], v[194:197], v[24:27]
	v_mfma_f32_16x16x32_bf16 v[16:19], v[170:173], v[202:205], v[16:19]
	v_mfma_f32_16x16x32_bf16 v[8:11], v[178:181], v[202:205], v[8:11]
	v_mfma_f32_16x16x32_bf16 v[4:7], v[170:173], v[214:217], v[4:7]
	v_mfma_f32_16x16x32_bf16 v[0:3], v[178:181], v[214:217], v[0:3]
	s_add_i32 s76, s76, 2
	s_add_u32 s28, s28, 0x40000
	s_addc_u32 s29, s29, 0
	s_add_u32 s72, s72, 0x800000
	s_addc_u32 s73, s73, 0
	s_cmp_gt_u32 s76, 29
	s_cbranch_scc0 .LBB0_770
	s_barrier
	s_and_b64 vcc, exec, s[38:39]
	s_cbranch_vccz .LBB0_773
	s_barrier
